# QKV GEMM: removed compiler-inserted per-iteration vmcnt(0) in mainloop; QKV epilogue: rope table loads prefetched one row-group ahead, store-draining vmcnt waits removed
# speedup vs baseline: 1.0070x; 1.0070x over previous
; #define PG8_STAGE(bufoff, gbase, voff) do { _Pragma("unroll") for (int _i = 0; _i < 2; ++_i) \
;         __builtin_amdgcn_global_load_lds((const unsigned*)((const char*)(gbase) + (voff)[_i]), (LAS unsigned*)(lds + (bufoff) + ldsw + _i * 8192), 16, 0, 0); } while (0)
; #define PG8_LDA(dst, b, h) do { _Pragma("unroll") for (int m = 0; m < 4; ++m) _Pragma("unroll") for (int k = 0; k < 2; ++k) dst[m][k] = *(const LAS bf16x8*)(lds + PG8_SA(b, h) + aoff + m * 2048 + k * 1024); } while (0)
; #define PG8_LDB(dst, b, h) do { _Pragma("unroll") for (int n = 0; n < 2; ++n) _Pragma("unroll") for (int k = 0; k < 2; ++k) dst[n][k] = *(const LAS bf16x8*)(lds + PG8_SB(b, h) + boff + n * 2048 + k * 1024); } while (0)
; #define PG8_MMA(ai, bj, At, Bt) do { __builtin_amdgcn_s_setprio(1); _Pragma("unroll") for (int m = 0; m < 4; ++m) _Pragma("unroll") for (int n = 0; n < 2; ++n) _Pragma("unroll") for (int k = 0; k < 2; ++k) \
;         acc[ai][bj][m][n] = __builtin_amdgcn_mfma_f32_16x16x32_bf16(Bt[n][k], At[m][k], acc[ai][bj][m][n], 0, 0, 0); __builtin_amdgcn_s_setprio(0); } while (0)
; #define PG8_WAIT_L(n) asm volatile("s_waitcnt lgkmcnt(" #n ")" ::: "memory")
; #define PG8_BAR __builtin_amdgcn_s_barrier()
; #define PG8_SCHED __builtin_amdgcn_sched_barrier(0)
; template <class Epi>
; __device__ __forceinline__ void gemm_phase(LAS unsigned char* lds, const Gemm g, const StaticOrder& S, const Epi& E, const int tid) {
;     ...
;         for (int t = 0; t < nt; t += 2) {
;             const bool last = (t == nt - 2);
;             const char* a1 = cA + (size_t)(t + 1) * kstep;
;             const char* a2 = last ? nA : cA + (size_t)(t + 2) * kstep; const char* b2 = last ? nB : cB + (size_t)(t + 2) * kstep;
;             const char* a3 = a2 + kstep; const char* b3 = b2 + kstep;
;             PG8_LDB(B0, 0, 0); PG8_SCHED; PG8_LDA(At, 0, 0); PG8_STAGE(PG8_SA(1, 1), a1 + hstep, voffA);
;             PG8_WAIT_L(8); PG8_BAR; PG8_WAIT_L(0); PG8_MMA(0, 0, At, B0); PG8_BAR; PG8_SCHED;
;             PG8_LDB(B1, 0, 1); PG8_STAGE(PG8_SB(0, 0), b2, voffB);
;             PG8_BAR; PG8_WAIT_L(0); PG8_MMA(0, 1, At, B1); PG8_BAR;
;             PG8_LDA(At, 0, 1); PG8_STAGE(PG8_SA(0, 0), a2, voffA);
;             PG8_BAR; PG8_WAIT_L(0); PG8_MMA(1, 0, At, B0); PG8_BAR; PG8_SCHED;
.LBB0_286:
	s_add_u32 s8, s6, 0xfff80080
	s_addc_u32 s9, s7, -1
	s_add_i32 s37, 0, 0x10000
	v_add_u32_e32 v0, s37, v210
	ds_read_b128 v[130:133], v0
	ds_read_b128 v[134:137], v0 offset:1024
	ds_read_b128 v[138:141], v0 offset:2048
	ds_read_b128 v[142:145], v0 offset:3072
	s_cmp_eq_u32 s36, 28
	s_cselect_b32 s35, s3, s9
	s_cselect_b32 s34, s27, s8
	s_cselect_b32 s9, s25, s72
	s_cselect_b32 s8, s50, s66
	v_lshl_add_u64 v[200:201], s[6:7], 0, v[170:171]
	s_add_i32 m0, s21, 0xc000
	ds_read_b128 v[172:175], v211
	ds_read_b128 v[176:179], v211 offset:1024
	ds_read_b128 v[180:183], v211 offset:2048
	ds_read_b128 v[184:187], v211 offset:3072
	ds_read_b128 v[188:191], v211 offset:4096
	ds_read_b128 v[192:195], v211 offset:5120
	ds_read_b128 v[196:199], v211 offset:6144
	ds_read_b128 v[212:215], v211 offset:7168
	global_load_lds_dwordx4 v[200:201], off
	v_lshl_add_u64 v[200:201], s[6:7], 0, v[168:169]
	s_add_i32 m0, s21, 0xe000
	s_nop 0
	global_load_lds_dwordx4 v[200:201], off
	s_waitcnt lgkmcnt(8)
	s_barrier
	s_waitcnt lgkmcnt(0)
	s_setprio 1
	s_waitcnt lgkmcnt(0)
	v_mfma_f32_16x16x32_bf16 v[126:129], v[130:133], v[172:175], v[126:129]
	v_mfma_f32_16x16x32_bf16 v[122:125], v[138:141], v[172:175], v[122:125]
	v_mfma_f32_16x16x32_bf16 v[118:121], v[130:133], v[180:183], v[118:121]
	v_mfma_f32_16x16x32_bf16 v[114:117], v[138:141], v[180:183], v[114:117]
	v_mfma_f32_16x16x32_bf16 v[102:105], v[130:133], v[188:191], v[102:105]
	v_mfma_f32_16x16x32_bf16 v[98:101], v[138:141], v[188:191], v[98:101]
	v_mfma_f32_16x16x32_bf16 v[86:89], v[130:133], v[196:199], v[86:89]
	v_mfma_f32_16x16x32_bf16 v[82:85], v[138:141], v[196:199], v[82:85]
	v_mfma_f32_16x16x32_bf16 v[126:129], v[134:137], v[176:179], v[126:129]
	v_mfma_f32_16x16x32_bf16 v[122:125], v[142:145], v[176:179], v[122:125]
	v_mfma_f32_16x16x32_bf16 v[118:121], v[134:137], v[184:187], v[118:121]
	v_mfma_f32_16x16x32_bf16 v[114:117], v[142:145], v[184:187], v[114:117]
	v_mfma_f32_16x16x32_bf16 v[102:105], v[134:137], v[192:195], v[102:105]
	v_mfma_f32_16x16x32_bf16 v[98:101], v[142:145], v[192:195], v[98:101]
	v_mfma_f32_16x16x32_bf16 v[86:89], v[134:137], v[212:215], v[86:89]
	v_mfma_f32_16x16x32_bf16 v[82:85], v[142:145], v[212:215], v[82:85]
	s_setprio 0
	s_barrier
	s_add_i32 s73, 0, 0x14000
	s_add_i32 s37, s37, s39
	v_add_u32_e32 v0, s73, v210
	v_lshl_add_u64 v[200:201], s[8:9], 0, v[162:163]
	s_mov_b32 m0, s37
	ds_read_b128 v[216:219], v0
	ds_read_b128 v[220:223], v0 offset:1024
	ds_read_b128 v[224:227], v0 offset:2048
	ds_read_b128 v[228:231], v0 offset:3072
	global_load_lds_dwordx4 v[200:201], off
	v_lshl_add_u64 v[232:233], s[8:9], 0, v[166:167]
	s_add_i32 m0, s37, 0x2000
	s_nop 0
	global_load_lds_dwordx4 v[232:233], off
	s_barrier
	s_waitcnt lgkmcnt(0)
	s_setprio 1
	s_waitcnt lgkmcnt(0)
	v_mfma_f32_16x16x32_bf16 v[110:113], v[216:219], v[172:175], v[110:113]
	v_mfma_f32_16x16x32_bf16 v[106:109], v[224:227], v[172:175], v[106:109]
	v_mfma_f32_16x16x32_bf16 v[94:97], v[216:219], v[180:183], v[94:97]
	v_mfma_f32_16x16x32_bf16 v[90:93], v[224:227], v[180:183], v[90:93]
	v_mfma_f32_16x16x32_bf16 v[78:81], v[216:219], v[188:191], v[78:81]
	v_mfma_f32_16x16x32_bf16 v[74:77], v[224:227], v[188:191], v[74:77]
	v_mfma_f32_16x16x32_bf16 v[70:73], v[216:219], v[196:199], v[70:73]
	v_mfma_f32_16x16x32_bf16 v[66:69], v[224:227], v[196:199], v[66:69]
	v_mfma_f32_16x16x32_bf16 v[110:113], v[220:223], v[176:179], v[110:113]
	v_mfma_f32_16x16x32_bf16 v[106:109], v[228:231], v[176:179], v[106:109]
	v_mfma_f32_16x16x32_bf16 v[94:97], v[220:223], v[184:187], v[94:97]
	v_mfma_f32_16x16x32_bf16 v[90:93], v[228:231], v[184:187], v[90:93]
	v_mfma_f32_16x16x32_bf16 v[78:81], v[220:223], v[192:195], v[78:81]
	v_mfma_f32_16x16x32_bf16 v[74:77], v[228:231], v[192:195], v[74:77]
	v_mfma_f32_16x16x32_bf16 v[70:73], v[220:223], v[212:215], v[70:73]
	v_mfma_f32_16x16x32_bf16 v[66:69], v[228:231], v[212:215], v[66:69]
	s_setprio 0
	s_mov_b32 m0, s21
	v_lshl_add_u64 v[234:235], s[34:35], 0, v[160:161]
	s_barrier
	ds_read_b128 v[172:175], v211 offset:16384
	ds_read_b128 v[176:179], v211 offset:17408
	ds_read_b128 v[180:183], v211 offset:18432
	ds_read_b128 v[184:187], v211 offset:19456
	ds_read_b128 v[188:191], v211 offset:20480
	ds_read_b128 v[192:195], v211 offset:21504
	ds_read_b128 v[196:199], v211 offset:22528
	ds_read_b128 v[212:215], v211 offset:23552
	global_load_lds_dwordx4 v[234:235], off
	v_lshl_add_u64 v[236:237], s[34:35], 0, v[164:165]
	s_mov_b32 m0, s40
	s_nop 0
	global_load_lds_dwordx4 v[236:237], off
	s_barrier
	s_waitcnt lgkmcnt(0)
	s_setprio 1
	s_waitcnt lgkmcnt(0)
	v_mfma_f32_16x16x32_bf16 v[62:65], v[130:133], v[172:175], v[62:65]
	v_mfma_f32_16x16x32_bf16 v[58:61], v[138:141], v[172:175], v[58:61]
	v_mfma_f32_16x16x32_bf16 v[54:57], v[130:133], v[180:183], v[54:57]
	v_mfma_f32_16x16x32_bf16 v[50:53], v[138:141], v[180:183], v[50:53]
	v_mfma_f32_16x16x32_bf16 v[38:41], v[130:133], v[188:191], v[38:41]
	v_mfma_f32_16x16x32_bf16 v[34:37], v[138:141], v[188:191], v[34:37]
	v_mfma_f32_16x16x32_bf16 v[22:25], v[130:133], v[196:199], v[22:25]
	v_mfma_f32_16x16x32_bf16 v[18:21], v[138:141], v[196:199], v[18:21]
	v_mfma_f32_16x16x32_bf16 v[62:65], v[134:137], v[176:179], v[62:65]
	v_mfma_f32_16x16x32_bf16 v[58:61], v[142:145], v[176:179], v[58:61]
	v_mfma_f32_16x16x32_bf16 v[54:57], v[134:137], v[184:187], v[54:57]
	v_mfma_f32_16x16x32_bf16 v[50:53], v[142:145], v[184:187], v[50:53]
	v_mfma_f32_16x16x32_bf16 v[38:41], v[134:137], v[192:195], v[38:41]
	v_mfma_f32_16x16x32_bf16 v[34:37], v[142:145], v[192:195], v[34:37]
	v_mfma_f32_16x16x32_bf16 v[22:25], v[134:137], v[212:215], v[22:25]
	v_mfma_f32_16x16x32_bf16 v[18:21], v[142:145], v[212:215], v[18:21]
	s_setprio 0
	s_barrier
; #define PG8_STAGE(bufoff, gbase, voff) do { _Pragma("unroll") for (int _i = 0; _i < 2; ++_i) \
;         __builtin_amdgcn_global_load_lds((const unsigned*)((const char*)(gbase) + (voff)[_i]), (LAS unsigned*)(lds + (bufoff) + ldsw + _i * 8192), 16, 0, 0); } while (0)
; #define PG8_LDA(dst, b, h) do { _Pragma("unroll") for (int m = 0; m < 4; ++m) _Pragma("unroll") for (int k = 0; k < 2; ++k) dst[m][k] = *(const LAS bf16x8*)(lds + PG8_SA(b, h) + aoff + m * 2048 + k * 1024); } while (0)
; #define PG8_LDB(dst, b, h) do { _Pragma("unroll") for (int n = 0; n < 2; ++n) _Pragma("unroll") for (int k = 0; k < 2; ++k) dst[n][k] = *(const LAS bf16x8*)(lds + PG8_SB(b, h) + boff + n * 2048 + k * 1024); } while (0)
; #define PG8_MMA(ai, bj, At, Bt) do { __builtin_amdgcn_s_setprio(1); _Pragma("unroll") for (int m = 0; m < 4; ++m) _Pragma("unroll") for (int n = 0; n < 2; ++n) _Pragma("unroll") for (int k = 0; k < 2; ++k) \
;         acc[ai][bj][m][n] = __builtin_amdgcn_mfma_f32_16x16x32_bf16(Bt[n][k], At[m][k], acc[ai][bj][m][n], 0, 0, 0); __builtin_amdgcn_s_setprio(0); } while (0)
; #define PG8_WAIT_V(n) asm volatile("s_waitcnt vmcnt(" #n ")" ::: "memory")
; #define PG8_WAIT_L(n) asm volatile("s_waitcnt lgkmcnt(" #n ")" ::: "memory")
; #define PG8_BAR __builtin_amdgcn_s_barrier()
; #define PG8_SCHED __builtin_amdgcn_sched_barrier(0)
; template <class Epi>
; __device__ __forceinline__ void gemm_phase(LAS unsigned char* lds, const Gemm g, const StaticOrder& S, const Epi& E, const int tid) {
;     ...
;             PG8_STAGE(PG8_SB(0, 1), b2 + hstep, voffB);
;             PG8_WAIT_V(6); PG8_BAR; PG8_MMA(1, 1, At, B1); PG8_BAR;
;             PG8_LDB(B0, 1, 0); PG8_SCHED; PG8_LDA(At, 1, 0); PG8_STAGE(PG8_SA(0, 1), a2 + hstep, voffA);
;             PG8_WAIT_L(8); PG8_BAR; PG8_WAIT_L(0); PG8_MMA(0, 0, At, B0); PG8_BAR; PG8_SCHED;
;             PG8_LDB(B1, 1, 1); PG8_STAGE(PG8_SB(1, 0), b3, voffB);
;             PG8_BAR; PG8_WAIT_L(0); PG8_MMA(0, 1, At, B1); PG8_BAR;
;             PG8_LDA(At, 1, 1); PG8_STAGE(PG8_SA(1, 0), a3, voffA);
	s_add_u32 s74, s8, 0x80000
	s_addc_u32 s75, s9, 0
	s_add_i32 s37, s73, s39
	v_lshl_add_u64 v[130:131], s[74:75], 0, v[162:163]
	s_mov_b32 m0, s37
	s_nop 0
	global_load_lds_dwordx4 v[130:131], off
	v_lshl_add_u64 v[130:131], s[74:75], 0, v[166:167]
	s_add_i32 m0, s37, 0x2000
	s_nop 0
	global_load_lds_dwordx4 v[130:131], off
	s_waitcnt vmcnt(6)
	s_barrier
	s_setprio 1
	v_mfma_f32_16x16x32_bf16 v[46:49], v[216:219], v[172:175], v[46:49]
	v_mfma_f32_16x16x32_bf16 v[42:45], v[224:227], v[172:175], v[42:45]
	v_mfma_f32_16x16x32_bf16 v[30:33], v[216:219], v[180:183], v[30:33]
	v_mfma_f32_16x16x32_bf16 v[26:29], v[224:227], v[180:183], v[26:29]
	v_mfma_f32_16x16x32_bf16 v[14:17], v[216:219], v[188:191], v[14:17]
	v_mfma_f32_16x16x32_bf16 v[10:13], v[224:227], v[188:191], v[10:13]
	v_mfma_f32_16x16x32_bf16 v[6:9], v[216:219], v[196:199], v[6:9]
	v_mfma_f32_16x16x32_bf16 v[2:5], v[224:227], v[196:199], v[2:5]
	v_mfma_f32_16x16x32_bf16 v[46:49], v[220:223], v[176:179], v[46:49]
	v_mfma_f32_16x16x32_bf16 v[42:45], v[228:231], v[176:179], v[42:45]
	v_mfma_f32_16x16x32_bf16 v[30:33], v[220:223], v[184:187], v[30:33]
	v_mfma_f32_16x16x32_bf16 v[26:29], v[228:231], v[184:187], v[26:29]
	v_mfma_f32_16x16x32_bf16 v[14:17], v[220:223], v[192:195], v[14:17]
	v_mfma_f32_16x16x32_bf16 v[10:13], v[228:231], v[192:195], v[10:13]
	v_mfma_f32_16x16x32_bf16 v[6:9], v[220:223], v[212:215], v[6:9]
	v_mfma_f32_16x16x32_bf16 v[2:5], v[228:231], v[212:215], v[2:5]
	s_setprio 0
	s_add_i32 s37, 0, 0x18000
	v_add_u32_e32 v0, s37, v210
	s_barrier
	ds_read_b128 v[130:133], v0
	ds_read_b128 v[134:137], v0 offset:1024
	ds_read_b128 v[138:141], v0 offset:2048
	ds_read_b128 v[142:145], v0 offset:3072
	s_add_u32 s34, s34, 0x80000
	s_addc_u32 s35, s35, 0
	s_mov_b32 m0, s41
	v_lshl_add_u64 v[216:217], s[34:35], 0, v[160:161]
	ds_read_b128 v[172:175], v211 offset:32768
	ds_read_b128 v[176:179], v211 offset:33792
	ds_read_b128 v[180:183], v211 offset:34816
	ds_read_b128 v[184:187], v211 offset:35840
	ds_read_b128 v[188:191], v211 offset:36864
	ds_read_b128 v[192:195], v211 offset:37888
	ds_read_b128 v[196:199], v211 offset:38912
	ds_read_b128 v[212:215], v211 offset:39936
	global_load_lds_dwordx4 v[216:217], off
	v_lshl_add_u64 v[216:217], s[34:35], 0, v[164:165]
	s_mov_b32 m0, s42
	s_nop 0
	global_load_lds_dwordx4 v[216:217], off
	s_waitcnt lgkmcnt(8)
	s_barrier
	s_waitcnt lgkmcnt(0)
	s_setprio 1
	s_waitcnt lgkmcnt(0)
	v_mfma_f32_16x16x32_bf16 v[126:129], v[130:133], v[172:175], v[126:129]
	v_mfma_f32_16x16x32_bf16 v[122:125], v[138:141], v[172:175], v[122:125]
	v_mfma_f32_16x16x32_bf16 v[118:121], v[130:133], v[180:183], v[118:121]
	v_mfma_f32_16x16x32_bf16 v[114:117], v[138:141], v[180:183], v[114:117]
	v_mfma_f32_16x16x32_bf16 v[102:105], v[130:133], v[188:191], v[102:105]
	v_mfma_f32_16x16x32_bf16 v[98:101], v[138:141], v[188:191], v[98:101]
	v_mfma_f32_16x16x32_bf16 v[86:89], v[130:133], v[196:199], v[86:89]
	v_mfma_f32_16x16x32_bf16 v[82:85], v[138:141], v[196:199], v[82:85]
	v_mfma_f32_16x16x32_bf16 v[126:129], v[134:137], v[176:179], v[126:129]
	v_mfma_f32_16x16x32_bf16 v[122:125], v[142:145], v[176:179], v[122:125]
	v_mfma_f32_16x16x32_bf16 v[118:121], v[134:137], v[184:187], v[118:121]
	v_mfma_f32_16x16x32_bf16 v[114:117], v[142:145], v[184:187], v[114:117]
	v_mfma_f32_16x16x32_bf16 v[102:105], v[134:137], v[192:195], v[102:105]
	v_mfma_f32_16x16x32_bf16 v[98:101], v[142:145], v[192:195], v[98:101]
	v_mfma_f32_16x16x32_bf16 v[86:89], v[134:137], v[212:215], v[86:89]
	v_mfma_f32_16x16x32_bf16 v[82:85], v[142:145], v[212:215], v[82:85]
	s_setprio 0
	s_barrier
	s_add_i32 s34, 0, 0x1c000
	s_add_i32 s35, s37, s39
	v_add_u32_e32 v0, s34, v210
	v_lshl_add_u64 v[200:201], v[200:201], 0, s[56:57]
	s_mov_b32 m0, s35
	ds_read_b128 v[216:219], v0
	ds_read_b128 v[220:223], v0 offset:1024
	ds_read_b128 v[224:227], v0 offset:2048
	ds_read_b128 v[228:231], v0 offset:3072
	global_load_lds_dwordx4 v[200:201], off
	v_lshl_add_u64 v[200:201], v[232:233], 0, s[56:57]
	s_add_i32 m0, s35, 0x2000
	s_nop 0
	global_load_lds_dwordx4 v[200:201], off
	s_barrier
	s_waitcnt lgkmcnt(0)
	s_setprio 1
	s_waitcnt lgkmcnt(0)
	v_mfma_f32_16x16x32_bf16 v[110:113], v[216:219], v[172:175], v[110:113]
	v_mfma_f32_16x16x32_bf16 v[106:109], v[224:227], v[172:175], v[106:109]
	v_mfma_f32_16x16x32_bf16 v[94:97], v[216:219], v[180:183], v[94:97]
	v_mfma_f32_16x16x32_bf16 v[90:93], v[224:227], v[180:183], v[90:93]
	v_mfma_f32_16x16x32_bf16 v[78:81], v[216:219], v[188:191], v[78:81]
	v_mfma_f32_16x16x32_bf16 v[74:77], v[224:227], v[188:191], v[74:77]
	v_mfma_f32_16x16x32_bf16 v[70:73], v[216:219], v[196:199], v[70:73]
	v_mfma_f32_16x16x32_bf16 v[66:69], v[224:227], v[196:199], v[66:69]
	v_mfma_f32_16x16x32_bf16 v[110:113], v[220:223], v[176:179], v[110:113]
	v_mfma_f32_16x16x32_bf16 v[106:109], v[228:231], v[176:179], v[106:109]
	v_mfma_f32_16x16x32_bf16 v[94:97], v[220:223], v[184:187], v[94:97]
	v_mfma_f32_16x16x32_bf16 v[90:93], v[228:231], v[184:187], v[90:93]
	v_mfma_f32_16x16x32_bf16 v[78:81], v[220:223], v[192:195], v[78:81]
	v_mfma_f32_16x16x32_bf16 v[74:77], v[228:231], v[192:195], v[74:77]
	v_mfma_f32_16x16x32_bf16 v[70:73], v[220:223], v[212:215], v[70:73]
	v_mfma_f32_16x16x32_bf16 v[66:69], v[228:231], v[212:215], v[66:69]
	s_setprio 0
	s_mov_b32 m0, s49
	v_lshl_add_u64 v[200:201], v[234:235], 0, s[56:57]
	s_barrier
; __device__ __forceinline__ unsigned pk2(float lo, float hi) { f32x2 v = {lo, hi}; return __builtin_bit_cast(unsigned, __builtin_convertvector(v, bf16x2_t)); }
; #define PG8_STAGE(bufoff, gbase, voff) do { _Pragma("unroll") for (int _i = 0; _i < 2; ++_i) \
;         __builtin_amdgcn_global_load_lds((const unsigned*)((const char*)(gbase) + (voff)[_i]), (LAS unsigned*)(lds + (bufoff) + ldsw + _i * 8192), 16, 0, 0); } while (0)
;     __device__ __forceinline__ void operator()(const f32x4 (&acc)[2][2][4][2], const Unit& u, int wr, int wc, int fr, int fq) const {
;     ...
;         const int type = (u.pn >> 2) % 3, grp = u.pn / 12;
;         const int row0 = u.pm * BM + wr * 64 + fr, col0 = u.pn * BM + wc * 32 + 8 * fq;
;         if (type == 2) {
; #pragma unroll
;             for (int ai = 0; ai < 2; ++ai)
; #pragma unroll
;                 for (int m = 0; m < 4; ++m) {
;                     bf16_t* rowp = O + ((size_t)(2 * u.pn) * MTOK + (row0 + ai * HALF + m * 16)) * 128 + wc * 32 + 8 * fq;
; #pragma unroll
;                     for (int bj = 0; bj < 2; ++bj) { const f32x4 v0 = acc[ai][bj][m][0], v1 = acc[ai][bj][m][1];
;                         u32x4 w; w.x = pk2(v0[0], v0[1]); w.y = pk2(v0[2], v0[3]); w.z = pk2(v1[0], v1[1]); w.w = pk2(v1[2], v1[3]); *(u32x4*)(rowp + (size_t)bj * MTOK * 128) = w; }
;                 }
;             return;
;         }
; #pragma unroll
;         for (int ai = 0; ai < 2; ++ai)
; #pragma unroll
;             for (int m = 0; m < 4; ++m)
; #pragma unroll
;                 for (int bj = 0; bj < 2; ++bj) {
;                     const f32x4 a = acc[ai][bj][m][0], b = acc[ai][bj][m][1];
;                     float s = (a[0] * a[0] + a[1] * a[1]) + (a[2] * a[2] + a[3] * a[3]) + (b[0] * b[0] + b[1] * b[1]) + (b[2] * b[2] + b[3] * b[3]);
;                     s += __shfl_xor(s, 16); s += __shfl_xor(s, 32);
;                     if (fq == 0) T[((wr * 128 + ai * 64 + m * 16 + fr) * 2 + bj) * 4 + wc] = s;
; template <class Epi>
; __device__ __forceinline__ void gemm_phase(LAS unsigned char* lds, const Gemm g, const StaticOrder& S, const Epi& E, const int tid) {
;     ...
;             PG8_LDA(At, 1, 1); PG8_STAGE(PG8_SA(1, 0), a3, voffA);
;             PG8_BAR; PG8_WAIT_L(0); PG8_MMA(1, 0, At, B0); PG8_BAR; PG8_SCHED;
;             PG8_STAGE(PG8_SB(1, 1), b3 + hstep, voffB);
;             PG8_WAIT_V(6); PG8_BAR; PG8_MMA(1, 1, At, B1); PG8_BAR;
	ds_read_b128 v[172:175], v211 offset:49152
	ds_read_b128 v[176:179], v211 offset:50176
	ds_read_b128 v[180:183], v211 offset:51200
	ds_read_b128 v[184:187], v211 offset:52224
	ds_read_b128 v[188:191], v211 offset:53248
	ds_read_b128 v[192:195], v211 offset:54272
	ds_read_b128 v[196:199], v211 offset:55296
	ds_read_b128 v[212:215], v211 offset:56320
	global_load_lds_dwordx4 v[200:201], off
	v_lshl_add_u64 v[200:201], v[236:237], 0, s[56:57]
	s_mov_b32 m0, s52
	s_nop 0
	global_load_lds_dwordx4 v[200:201], off
	s_barrier
	s_waitcnt lgkmcnt(0)
	s_setprio 1
	s_waitcnt lgkmcnt(0)
	v_mfma_f32_16x16x32_bf16 v[62:65], v[130:133], v[172:175], v[62:65]
	v_mfma_f32_16x16x32_bf16 v[58:61], v[138:141], v[172:175], v[58:61]
	v_mfma_f32_16x16x32_bf16 v[54:57], v[130:133], v[180:183], v[54:57]
	v_mfma_f32_16x16x32_bf16 v[50:53], v[138:141], v[180:183], v[50:53]
	v_mfma_f32_16x16x32_bf16 v[38:41], v[130:133], v[188:191], v[38:41]
	v_mfma_f32_16x16x32_bf16 v[34:37], v[138:141], v[188:191], v[34:37]
	v_mfma_f32_16x16x32_bf16 v[22:25], v[130:133], v[196:199], v[22:25]
	v_mfma_f32_16x16x32_bf16 v[18:21], v[138:141], v[196:199], v[18:21]
	v_mfma_f32_16x16x32_bf16 v[62:65], v[134:137], v[176:179], v[62:65]
	v_mfma_f32_16x16x32_bf16 v[58:61], v[142:145], v[176:179], v[58:61]
	v_mfma_f32_16x16x32_bf16 v[54:57], v[134:137], v[184:187], v[54:57]
	v_mfma_f32_16x16x32_bf16 v[50:53], v[142:145], v[184:187], v[50:53]
	v_mfma_f32_16x16x32_bf16 v[38:41], v[134:137], v[192:195], v[38:41]
	v_mfma_f32_16x16x32_bf16 v[34:37], v[142:145], v[192:195], v[34:37]
	v_mfma_f32_16x16x32_bf16 v[22:25], v[134:137], v[212:215], v[22:25]
	v_mfma_f32_16x16x32_bf16 v[18:21], v[142:145], v[212:215], v[18:21]
	s_setprio 0
	s_barrier
	s_add_u32 s8, s8, 0x80080
	s_addc_u32 s9, s9, 0
	s_add_i32 s34, s34, s39
	v_lshl_add_u64 v[130:131], s[8:9], 0, v[162:163]
	s_mov_b32 m0, s34
	s_nop 0
	global_load_lds_dwordx4 v[130:131], off
	v_lshl_add_u64 v[130:131], s[8:9], 0, v[166:167]
	s_add_i32 m0, s34, 0x2000
	s_nop 0
	global_load_lds_dwordx4 v[130:131], off
	s_waitcnt vmcnt(6)
	s_barrier
	s_setprio 1
	v_mfma_f32_16x16x32_bf16 v[46:49], v[216:219], v[172:175], v[46:49]
	v_mfma_f32_16x16x32_bf16 v[42:45], v[224:227], v[172:175], v[42:45]
	v_mfma_f32_16x16x32_bf16 v[30:33], v[216:219], v[180:183], v[30:33]
	v_mfma_f32_16x16x32_bf16 v[26:29], v[224:227], v[180:183], v[26:29]
	v_mfma_f32_16x16x32_bf16 v[14:17], v[216:219], v[188:191], v[14:17]
	v_mfma_f32_16x16x32_bf16 v[10:13], v[224:227], v[188:191], v[10:13]
	v_mfma_f32_16x16x32_bf16 v[6:9], v[216:219], v[196:199], v[6:9]
	v_mfma_f32_16x16x32_bf16 v[2:5], v[224:227], v[196:199], v[2:5]
	v_mfma_f32_16x16x32_bf16 v[46:49], v[220:223], v[176:179], v[46:49]
	v_mfma_f32_16x16x32_bf16 v[42:45], v[228:231], v[176:179], v[42:45]
	v_mfma_f32_16x16x32_bf16 v[30:33], v[220:223], v[184:187], v[30:33]
	v_mfma_f32_16x16x32_bf16 v[26:29], v[228:231], v[184:187], v[26:29]
	v_mfma_f32_16x16x32_bf16 v[14:17], v[220:223], v[192:195], v[14:17]
	v_mfma_f32_16x16x32_bf16 v[10:13], v[228:231], v[192:195], v[10:13]
	v_mfma_f32_16x16x32_bf16 v[6:9], v[220:223], v[212:215], v[6:9]
	v_mfma_f32_16x16x32_bf16 v[2:5], v[228:231], v[212:215], v[2:5]
	s_setprio 0
	s_add_i32 s36, s36, 2
	s_add_u32 s66, s66, 0x100
	s_addc_u32 s72, s72, 0
	s_add_u32 s6, s6, 0x100
	s_addc_u32 s7, s7, 0
	s_cmp_gt_u32 s36, 29
	s_barrier
	s_cbranch_scc0 .LBB0_286
	s_ashr_i32 s3, s20, 2
	s_mul_hi_i32 s6, s3, 0x55555556
	s_lshr_b32 s7, s6, 31
	s_add_i32 s6, s6, s7
	s_mul_i32 s6, s6, 3
	s_lshl_b32 s2, s2, 8
	v_mov_b32_e32 v138, v159
	v_mov_b32_e32 v0, v209
	s_sub_i32 s6, s3, s6
	s_add_i32 s2, s2, s47
	s_cmp_eq_u32 s6, 2
	v_add_u32_e32 v174, s2, v138
	v_lshlrev_b32_e32 v172, 3, v0
	s_mov_b64 s[2:3], -1
	s_cbranch_scc1 .LBB0_376
	v_mul_f32_e32 v132, v127, v127
	v_mul_f32_e32 v133, v129, v129
	v_fmac_f32_e32 v132, v126, v126
	v_fmac_f32_e32 v133, v128, v128
	v_and_b32_e32 v131, 64, v204
	v_add_f32_e32 v132, v132, v133
	v_mul_f32_e32 v133, v123, v123
	v_xor_b32_e32 v130, 16, v204
	v_add_u32_e32 v131, 64, v131
	v_fmac_f32_e32 v133, v122, v122
	v_cmp_lt_i32_e32 vcc, v130, v131
	v_add_f32_e32 v132, v132, v133
	v_mul_f32_e32 v133, v125, v125
	v_cndmask_b32_e32 v130, v204, v130, vcc
	v_fmac_f32_e32 v133, v124, v124
	v_lshlrev_b32_e32 v130, 2, v130
	v_add_f32_e32 v132, v133, v132
	ds_bpermute_b32 v133, v130, v132
	v_xor_b32_e32 v134, 32, v204
	v_cmp_lt_i32_e32 vcc, v134, v131
	v_lshlrev_b32_e32 v175, 5, v138
	s_waitcnt lgkmcnt(0)
	v_add_f32_e32 v132, v132, v133
	v_cndmask_b32_e32 v131, v204, v134, vcc
	v_lshlrev_b32_e32 v212, 2, v131
	ds_bpermute_b32 v133, v212, v132
	v_cmp_eq_u32_e32 vcc, 0, v0
	v_add_u32_e32 v131, s63, v175
	s_and_saveexec_b64 s[2:3], vcc
	s_cbranch_execz .LBB0_290
	s_waitcnt lgkmcnt(0)
	v_add_f32_e32 v132, v132, v133
	ds_write_b32 v131, v132

; #define LAS __attribute__((address_space(3)))
;     __device__ __forceinline__ void operator()(const f32x4 (&acc)[2][2][4][2], const Unit& u, int wr, int wc, int fr, int fq) const {
;     ...
;                 const int row = row0 + ai * HALF + m * 16;
;                 f32x4 cs[2] = {{1.f, 1.f, 1.f, 1.f}, {1.f, 1.f, 1.f, 1.f}}, sn[2] = {{0.f, 0.f, 0.f, 0.f}, {0.f, 0.f, 0.f, 0.f}};
;                 if (dorope) { const float* rp = rope + (size_t)(row & (SEQ - 1)) * 32 + 8 * (fq & 1);
;                     cs[0] = *(const f32x4*)rp; cs[1] = *(const f32x4*)(rp + 4); sn[0] = *(const f32x4*)(rp + 16); sn[1] = *(const f32x4*)(rp + 20);
;                     sn[0] = sn[0] * sgn; sn[1] = sn[1] * sgn; }
;                 bf16_t* rowp = O + ((size_t)(2 * u.pn) * MTOK + row) * 128 + wc * 32 + 8 * fq;
; #pragma unroll
;                 for (int bj = 0; bj < 2; ++bj) {
;                     const f32x4 t4 = *(const LAS f32x4*)(T + ((wr * 128 + ai * 64 + m * 16 + fr) * 2 + bj) * 4);
;                     const float rstd = rsqrtf(((t4[0] + t4[1]) + (t4[2] + t4[3])) * (1.0f / 128.0f) + EPSN);
;                     f32x4 v0 = acc[ai][bj][m][0] * rstd * gm[0], v1 = acc[ai][bj][m][1] * rstd * gm[1];
;                     if (dorope) {
;                         f32x4 p0, p1;
; #pragma unroll
;                         for (int e = 0; e < 4; ++e) { p0[e] = __shfl_xor(v0[e], 32); p1[e] = __shfl_xor(v1[e], 32); }
;                         v0 = v0 * cs[0] + p0 * sn[0]; v1 = v1 * cs[1] + p1 * sn[1];
.LBB0_322:
	v_add_u32_e32 v213, s62, v175
	ds_read_b128 v[190:193], v213
	s_waitcnt lgkmcnt(0)
	v_mov_b32_e32 v176, v191
	v_mov_b32_e32 v177, v192
	v_mov_b32_e32 v191, v193
	v_pk_add_f32 v[176:177], v[176:177], v[190:191]
	s_nop 0
	v_add_f32_e32 v0, v176, v177
	v_fmamk_f32 v0, v0, 0x3c000000, v203
	v_mul_f32_e32 v175, 0x4b800000, v0
	v_cmp_gt_f32_e32 vcc, s89, v0
	s_nop 1
	v_cndmask_b32_e32 v0, v0, v175, vcc
	v_rsq_f32_e32 v0, v0
	s_nop 0
	v_mul_f32_e32 v175, 0x45800000, v0
	v_cndmask_b32_e32 v0, v0, v175, vcc
	v_pk_mul_f32 v[176:177], v[126:127], v[0:1] op_sel_hi:[1,0]
	v_pk_mul_f32 v[190:191], v[128:129], v[0:1] op_sel_hi:[1,0]
	v_pk_mul_f32 v[198:199], v[122:123], v[0:1] op_sel_hi:[1,0]
	v_pk_mul_f32 v[196:197], v[124:125], v[0:1] op_sel_hi:[1,0]
	s_waitcnt vmcnt(0)
	v_pk_mul_f32 v[192:193], v[136:137], v[190:191]
	v_pk_mul_f32 v[194:195], v[134:135], v[176:177]
	v_pk_mul_f32 v[196:197], v[132:133], v[196:197]
	s_and_b64 vcc, exec, s[6:7]
	v_pk_mul_f32 v[198:199], v[130:131], v[198:199]
	s_cbranch_vccnz .LBB0_324
	v_add_u32_e32 v0, 0x10, v174
	v_lshlrev_b32_e32 v0, 7, v0
	v_and_b32_e32 v0, 0xfff80, v0
	v_add_u32_e32 v0, v0, v180
	global_load_dwordx4 v[222:225], v0, s[18:19] offset:64
	global_load_dwordx4 v[226:229], v0, s[18:19] offset:80
	global_load_dwordx4 v[230:233], v0, s[18:19] offset:16
	global_load_dwordx4 v[234:237], v0, s[18:19]
	ds_bpermute_b32 v176, v212, v194
	ds_bpermute_b32 v177, v212, v195
	ds_bpermute_b32 v190, v212, v198
	ds_bpermute_b32 v200, v212, v192
	ds_bpermute_b32 v201, v212, v193
	ds_bpermute_b32 v191, v212, v199
	ds_bpermute_b32 v214, v212, v196
	ds_bpermute_b32 v215, v212, v197
	s_waitcnt lgkmcnt(6)
	v_pk_mul_f32 v[176:177], v[188:189], v[176:177]
	s_waitcnt lgkmcnt(3)
	v_pk_mul_f32 v[200:201], v[186:187], v[200:201]
	v_pk_fma_f32 v[194:195], v[142:143], v[194:195], v[176:177]
	s_waitcnt lgkmcnt(2)
	v_pk_mul_f32 v[176:177], v[182:183], v[190:191]
	s_waitcnt lgkmcnt(0)
	v_pk_mul_f32 v[190:191], v[184:185], v[214:215]
	v_pk_fma_f32 v[192:193], v[144:145], v[192:193], v[200:201]
	v_pk_fma_f32 v[196:197], v[140:141], v[196:197], v[190:191]
	v_pk_fma_f32 v[198:199], v[138:139], v[198:199], v[176:177]

; #define LAS __attribute__((address_space(3)))
; __device__ __forceinline__ unsigned pk2(float lo, float hi) { f32x2 v = {lo, hi}; return __builtin_bit_cast(unsigned, __builtin_convertvector(v, bf16x2_t)); }
;     __device__ __forceinline__ void operator()(const f32x4 (&acc)[2][2][4][2], const Unit& u, int wr, int wc, int fr, int fq) const {
;     ...
;                 const int row = row0 + ai * HALF + m * 16;
;                 f32x4 cs[2] = {{1.f, 1.f, 1.f, 1.f}, {1.f, 1.f, 1.f, 1.f}}, sn[2] = {{0.f, 0.f, 0.f, 0.f}, {0.f, 0.f, 0.f, 0.f}};
;                 if (dorope) { const float* rp = rope + (size_t)(row & (SEQ - 1)) * 32 + 8 * (fq & 1);
;                     cs[0] = *(const f32x4*)rp; cs[1] = *(const f32x4*)(rp + 4); sn[0] = *(const f32x4*)(rp + 16); sn[1] = *(const f32x4*)(rp + 20);
;                     sn[0] = sn[0] * sgn; sn[1] = sn[1] * sgn; }
;                 bf16_t* rowp = O + ((size_t)(2 * u.pn) * MTOK + row) * 128 + wc * 32 + 8 * fq;
; #pragma unroll
;                 for (int bj = 0; bj < 2; ++bj) {
;                     const f32x4 t4 = *(const LAS f32x4*)(T + ((wr * 128 + ai * 64 + m * 16 + fr) * 2 + bj) * 4);
;                     const float rstd = rsqrtf(((t4[0] + t4[1]) + (t4[2] + t4[3])) * (1.0f / 128.0f) + EPSN);
;                     f32x4 v0 = acc[ai][bj][m][0] * rstd * gm[0], v1 = acc[ai][bj][m][1] * rstd * gm[1];
;                     if (dorope) {
;                         f32x4 p0, p1;
; #pragma unroll
;                         for (int e = 0; e < 4; ++e) { p0[e] = __shfl_xor(v0[e], 32); p1[e] = __shfl_xor(v1[e], 32); }
;                         v0 = v0 * cs[0] + p0 * sn[0]; v1 = v1 * cs[1] + p1 * sn[1];
;                     }
;                     v0 = v0 * mul; v1 = v1 * mul;
;                     u32x4 w; w.x = pk2(v0[0], v0[1]); w.y = pk2(v0[2], v0[3]); w.z = pk2(v1[0], v1[1]); w.w = pk2(v1[2], v1[3]);
;                     *(u32x4*)(rowp + (size_t)bj * MTOK * 128) = w;
.LBB0_326:
	v_mov_b32_e32 v177, v176
	v_mov_b32_e32 v138, v176
	v_mov_b32_e32 v139, v176
	v_pk_mul_f32 v[142:143], v[176:177], v[194:195]
	v_pk_mul_f32 v[140:141], v[138:139], v[192:193]
	v_pk_mul_f32 v[144:145], v[138:139], v[196:197]
	v_cvt_pk_bf16_f32 v138, v142, v143
	v_add_co_u32_e32 v142, vcc, 0x800000, v190
	v_pk_mul_f32 v[182:183], v[176:177], v[198:199]
	s_nop 0
	v_addc_co_u32_e32 v143, vcc, 0, v191, vcc
	v_cvt_pk_bf16_f32 v139, v140, v141
	v_cvt_pk_bf16_f32 v140, v182, v183
	v_cvt_pk_bf16_f32 v141, v144, v145
	s_and_b64 vcc, exec, s[6:7]
	v_add_u32_e32 v190, 16, v174
	global_store_dwordx4 v[142:143], v[138:141], off
	s_cbranch_vccnz .LBB0_328
	s_waitcnt vmcnt(2)
	v_mov_b32_e32 v196, v178
	v_mov_b32_e32 v197, v178
	v_pk_mul_f32 v[186:187], v[196:197], v[224:225]
	v_pk_mul_f32 v[188:189], v[178:179], v[222:223]
	v_pk_mul_f32 v[184:185], v[196:197], v[228:229]
	v_pk_mul_f32 v[182:183], v[178:179], v[226:227]
	v_mov_b32_e32 v138, v230
	v_mov_b32_e32 v139, v231
	v_mov_b32_e32 v140, v232
	v_mov_b32_e32 v141, v233
	v_mov_b32_e32 v142, v234
	v_mov_b32_e32 v143, v235
	v_mov_b32_e32 v144, v236
	v_mov_b32_e32 v145, v237
	v_add_u32_e32 v0, 0x20, v174
	v_lshlrev_b32_e32 v0, 7, v0
	v_and_b32_e32 v0, 0xfff80, v0
	v_add_u32_e32 v0, v0, v180
	global_load_dwordx4 v[222:225], v0, s[18:19] offset:64
	global_load_dwordx4 v[226:229], v0, s[18:19] offset:80
	global_load_dwordx4 v[230:233], v0, s[18:19] offset:16
	global_load_dwordx4 v[234:237], v0, s[18:19]
	s_branch .LBB0_329

; #define LAS __attribute__((address_space(3)))
; __device__ __forceinline__ unsigned pk2(float lo, float hi) { f32x2 v = {lo, hi}; return __builtin_bit_cast(unsigned, __builtin_convertvector(v, bf16x2_t)); }
;     __device__ __forceinline__ void operator()(const f32x4 (&acc)[2][2][4][2], const Unit& u, int wr, int wc, int fr, int fq) const {
;     ...
;                 const int row = row0 + ai * HALF + m * 16;
;                 f32x4 cs[2] = {{1.f, 1.f, 1.f, 1.f}, {1.f, 1.f, 1.f, 1.f}}, sn[2] = {{0.f, 0.f, 0.f, 0.f}, {0.f, 0.f, 0.f, 0.f}};
;                 if (dorope) { const float* rp = rope + (size_t)(row & (SEQ - 1)) * 32 + 8 * (fq & 1);
;                     cs[0] = *(const f32x4*)rp; cs[1] = *(const f32x4*)(rp + 4); sn[0] = *(const f32x4*)(rp + 16); sn[1] = *(const f32x4*)(rp + 20);
;                     sn[0] = sn[0] * sgn; sn[1] = sn[1] * sgn; }
;                 bf16_t* rowp = O + ((size_t)(2 * u.pn) * MTOK + row) * 128 + wc * 32 + 8 * fq;
; #pragma unroll
;                 for (int bj = 0; bj < 2; ++bj) {
;                     const f32x4 t4 = *(const LAS f32x4*)(T + ((wr * 128 + ai * 64 + m * 16 + fr) * 2 + bj) * 4);
;                     const float rstd = rsqrtf(((t4[0] + t4[1]) + (t4[2] + t4[3])) * (1.0f / 128.0f) + EPSN);
;                     f32x4 v0 = acc[ai][bj][m][0] * rstd * gm[0], v1 = acc[ai][bj][m][1] * rstd * gm[1];
;                     if (dorope) {
;                         f32x4 p0, p1;
; #pragma unroll
;                         for (int e = 0; e < 4; ++e) { p0[e] = __shfl_xor(v0[e], 32); p1[e] = __shfl_xor(v1[e], 32); }
;                         v0 = v0 * cs[0] + p0 * sn[0]; v1 = v1 * cs[1] + p1 * sn[1];
;                     }
;                     v0 = v0 * mul; v1 = v1 * mul;
;                     u32x4 w; w.x = pk2(v0[0], v0[1]); w.y = pk2(v0[2], v0[3]); w.z = pk2(v1[0], v1[1]); w.w = pk2(v1[2], v1[3]);
;                     *(u32x4*)(rowp + (size_t)bj * MTOK * 128) = w;
.LBB0_329:
	ds_read_b128 v[192:195], v213 offset:512
	s_waitcnt lgkmcnt(0)
	v_mov_b32_e32 v196, v193
	v_mov_b32_e32 v197, v194
	v_mov_b32_e32 v193, v195
	v_pk_add_f32 v[192:193], v[196:197], v[192:193]
	s_nop 0
	v_add_f32_e32 v0, v192, v193
	v_fmamk_f32 v0, v0, 0x3c000000, v203
	v_mul_f32_e32 v175, 0x4b800000, v0
	v_cmp_gt_f32_e32 vcc, s89, v0
	s_nop 1
	v_cndmask_b32_e32 v0, v0, v175, vcc
	v_rsq_f32_e32 v0, v0
	s_nop 0
	v_mul_f32_e32 v175, 0x45800000, v0
	v_cndmask_b32_e32 v0, v0, v175, vcc
	v_pk_mul_f32 v[192:193], v[118:119], v[0:1] op_sel_hi:[1,0]
	v_pk_mul_f32 v[194:195], v[120:121], v[0:1] op_sel_hi:[1,0]
	v_pk_mul_f32 v[200:201], v[114:115], v[0:1] op_sel_hi:[1,0]
	v_pk_mul_f32 v[198:199], v[116:117], v[0:1] op_sel_hi:[1,0]
	v_pk_mul_f32 v[194:195], v[136:137], v[194:195]
	v_pk_mul_f32 v[196:197], v[134:135], v[192:193]
	v_pk_mul_f32 v[198:199], v[132:133], v[198:199]
	s_and_b64 vcc, exec, s[6:7]
	v_pk_mul_f32 v[200:201], v[130:131], v[200:201]
	s_cbranch_vccnz .LBB0_331
	ds_bpermute_b32 v192, v212, v196
	ds_bpermute_b32 v193, v212, v197
	ds_bpermute_b32 v214, v212, v200
	ds_bpermute_b32 v216, v212, v194
	ds_bpermute_b32 v217, v212, v195
	ds_bpermute_b32 v215, v212, v201
	ds_bpermute_b32 v218, v212, v198
	ds_bpermute_b32 v219, v212, v199
	s_waitcnt lgkmcnt(6)
	v_pk_mul_f32 v[192:193], v[188:189], v[192:193]
	s_waitcnt lgkmcnt(3)
	v_pk_mul_f32 v[216:217], v[186:187], v[216:217]
	v_pk_fma_f32 v[196:197], v[142:143], v[196:197], v[192:193]
	s_waitcnt lgkmcnt(2)
	v_pk_mul_f32 v[192:193], v[182:183], v[214:215]
	s_waitcnt lgkmcnt(0)
	v_pk_mul_f32 v[214:215], v[184:185], v[218:219]
	v_pk_fma_f32 v[194:195], v[144:145], v[194:195], v[216:217]
	v_pk_fma_f32 v[198:199], v[140:141], v[198:199], v[214:215]
	v_pk_fma_f32 v[200:201], v[138:139], v[200:201], v[192:193]
.LBB0_331:
	v_ashrrev_i32_e32 v191, 31, v190
	v_lshlrev_b64 v[190:191], 8, v[190:191]
	v_lshl_add_u64 v[190:191], s[34:35], 0, v[190:191]
	v_mov_b32_e32 v192, v176
	v_mov_b32_e32 v193, v176
	v_lshl_add_u64 v[190:191], v[190:191], 0, s[50:51]
	v_pk_mul_f32 v[214:215], v[192:193], v[194:195]
	v_pk_mul_f32 v[194:195], v[176:177], v[196:197]
	v_pk_mul_f32 v[198:199], v[192:193], v[198:199]
	v_pk_mul_f32 v[196:197], v[176:177], v[200:201]
	v_lshl_add_u64 v[190:191], v[172:173], 1, v[190:191]
	v_cvt_pk_bf16_f32 v194, v194, v195
	v_cvt_pk_bf16_f32 v195, v214, v215
	v_cvt_pk_bf16_f32 v196, v196, v197
	v_cvt_pk_bf16_f32 v197, v198, v199
	global_store_dwordx4 v[190:191], v[194:197], off
	ds_read_b128 v[194:197], v213 offset:528
	s_waitcnt lgkmcnt(0)
	v_mov_b32_e32 v198, v195
	v_mov_b32_e32 v199, v196
	v_mov_b32_e32 v195, v197
	v_pk_add_f32 v[194:195], v[198:199], v[194:195]
	s_nop 0
	v_add_f32_e32 v0, v194, v195
	v_fmamk_f32 v0, v0, 0x3c000000, v203
	v_cmp_gt_f32_e32 vcc, s89, v0
	v_mul_f32_e32 v175, 0x4b800000, v0
	s_nop 0
	v_cndmask_b32_e32 v0, v0, v175, vcc
	v_rsq_f32_e32 v0, v0
	s_nop 0
	v_mul_f32_e32 v175, 0x45800000, v0
	v_cndmask_b32_e32 v0, v0, v175, vcc
	v_pk_mul_f32 v[196:197], v[94:95], v[0:1] op_sel_hi:[1,0]
	v_pk_mul_f32 v[194:195], v[96:97], v[0:1] op_sel_hi:[1,0]
	v_pk_mul_f32 v[200:201], v[90:91], v[0:1] op_sel_hi:[1,0]
	v_pk_mul_f32 v[198:199], v[92:93], v[0:1] op_sel_hi:[1,0]
	v_pk_mul_f32 v[194:195], v[136:137], v[194:195]
	v_pk_mul_f32 v[196:197], v[134:135], v[196:197]
	v_pk_mul_f32 v[198:199], v[132:133], v[198:199]
	v_pk_mul_f32 v[200:201], v[130:131], v[200:201]
	s_and_b64 vcc, exec, s[6:7]
	s_cbranch_vccnz .LBB0_333
	ds_bpermute_b32 v214, v212, v196
	ds_bpermute_b32 v215, v212, v197
	ds_bpermute_b32 v218, v212, v194
	ds_bpermute_b32 v219, v212, v195
	ds_bpermute_b32 v216, v212, v200
	ds_bpermute_b32 v217, v212, v201
	ds_bpermute_b32 v220, v212, v198
	ds_bpermute_b32 v221, v212, v199
	s_waitcnt lgkmcnt(6)
	v_pk_mul_f32 v[188:189], v[188:189], v[214:215]
	s_waitcnt lgkmcnt(4)
	v_pk_mul_f32 v[186:187], v[186:187], v[218:219]
	v_pk_fma_f32 v[196:197], v[142:143], v[196:197], v[188:189]
	v_pk_fma_f32 v[194:195], v[144:145], v[194:195], v[186:187]
	s_waitcnt lgkmcnt(2)
	v_pk_mul_f32 v[142:143], v[182:183], v[216:217]
	s_waitcnt lgkmcnt(0)
	v_pk_mul_f32 v[144:145], v[184:185], v[220:221]
	v_pk_fma_f32 v[200:201], v[138:139], v[200:201], v[142:143]
	v_pk_fma_f32 v[198:199], v[140:141], v[198:199], v[144:145]
.LBB0_333:
	v_pk_mul_f32 v[140:141], v[192:193], v[194:195]
	v_pk_mul_f32 v[138:139], v[176:177], v[196:197]
	v_pk_mul_f32 v[142:143], v[192:193], v[198:199]
	v_cvt_pk_bf16_f32 v138, v138, v139
	v_cvt_pk_bf16_f32 v139, v140, v141
	v_cvt_pk_bf16_f32 v141, v142, v143
	v_add_co_u32_e32 v142, vcc, 0x800000, v190
	v_pk_mul_f32 v[144:145], v[176:177], v[200:201]
	s_nop 0
	v_addc_co_u32_e32 v143, vcc, 0, v191, vcc
	v_cvt_pk_bf16_f32 v140, v144, v145
	s_and_b64 vcc, exec, s[6:7]
	v_add_u32_e32 v190, 32, v174
	global_store_dwordx4 v[142:143], v[138:141], off
	s_cbranch_vccnz .LBB0_335
	s_waitcnt vmcnt(2)
	v_mov_b32_e32 v196, v178
	v_mov_b32_e32 v197, v178
	v_pk_mul_f32 v[186:187], v[196:197], v[224:225]
	v_pk_mul_f32 v[188:189], v[178:179], v[222:223]
	v_pk_mul_f32 v[184:185], v[196:197], v[228:229]
	v_pk_mul_f32 v[182:183], v[178:179], v[226:227]
	v_mov_b32_e32 v138, v230
	v_mov_b32_e32 v139, v231
	v_mov_b32_e32 v140, v232
	v_mov_b32_e32 v141, v233
	v_mov_b32_e32 v142, v234
	v_mov_b32_e32 v143, v235
	v_mov_b32_e32 v144, v236
	v_mov_b32_e32 v145, v237
	v_add_u32_e32 v0, 0x30, v174
	v_lshlrev_b32_e32 v0, 7, v0
	v_and_b32_e32 v0, 0xfff80, v0
	v_add_u32_e32 v0, v0, v180
	global_load_dwordx4 v[222:225], v0, s[18:19] offset:64
	global_load_dwordx4 v[226:229], v0, s[18:19] offset:80
	global_load_dwordx4 v[230:233], v0, s[18:19] offset:16
	global_load_dwordx4 v[234:237], v0, s[18:19]
	s_branch .LBB0_336

; #define LAS __attribute__((address_space(3)))
; __device__ __forceinline__ unsigned pk2(float lo, float hi) { f32x2 v = {lo, hi}; return __builtin_bit_cast(unsigned, __builtin_convertvector(v, bf16x2_t)); }
;     __device__ __forceinline__ void operator()(const f32x4 (&acc)[2][2][4][2], const Unit& u, int wr, int wc, int fr, int fq) const {
;     ...
;                 const int row = row0 + ai * HALF + m * 16;
;                 f32x4 cs[2] = {{1.f, 1.f, 1.f, 1.f}, {1.f, 1.f, 1.f, 1.f}}, sn[2] = {{0.f, 0.f, 0.f, 0.f}, {0.f, 0.f, 0.f, 0.f}};
;                 if (dorope) { const float* rp = rope + (size_t)(row & (SEQ - 1)) * 32 + 8 * (fq & 1);
;                     cs[0] = *(const f32x4*)rp; cs[1] = *(const f32x4*)(rp + 4); sn[0] = *(const f32x4*)(rp + 16); sn[1] = *(const f32x4*)(rp + 20);
;                     sn[0] = sn[0] * sgn; sn[1] = sn[1] * sgn; }
;                 bf16_t* rowp = O + ((size_t)(2 * u.pn) * MTOK + row) * 128 + wc * 32 + 8 * fq;
; #pragma unroll
;                 for (int bj = 0; bj < 2; ++bj) {
;                     const f32x4 t4 = *(const LAS f32x4*)(T + ((wr * 128 + ai * 64 + m * 16 + fr) * 2 + bj) * 4);
;                     const float rstd = rsqrtf(((t4[0] + t4[1]) + (t4[2] + t4[3])) * (1.0f / 128.0f) + EPSN);
;                     f32x4 v0 = acc[ai][bj][m][0] * rstd * gm[0], v1 = acc[ai][bj][m][1] * rstd * gm[1];
;                     if (dorope) {
;                         f32x4 p0, p1;
; #pragma unroll
;                         for (int e = 0; e < 4; ++e) { p0[e] = __shfl_xor(v0[e], 32); p1[e] = __shfl_xor(v1[e], 32); }
;                         v0 = v0 * cs[0] + p0 * sn[0]; v1 = v1 * cs[1] + p1 * sn[1];
;                     }
;                     v0 = v0 * mul; v1 = v1 * mul;
;                     u32x4 w; w.x = pk2(v0[0], v0[1]); w.y = pk2(v0[2], v0[3]); w.z = pk2(v1[0], v1[1]); w.w = pk2(v1[2], v1[3]);
;                     *(u32x4*)(rowp + (size_t)bj * MTOK * 128) = w;
.LBB0_336:
	ds_read_b128 v[192:195], v213 offset:1024
	s_waitcnt lgkmcnt(0)
	v_mov_b32_e32 v196, v193
	v_mov_b32_e32 v197, v194
	v_mov_b32_e32 v193, v195
	v_pk_add_f32 v[192:193], v[196:197], v[192:193]
	s_nop 0
	v_add_f32_e32 v0, v192, v193
	v_fmamk_f32 v0, v0, 0x3c000000, v203
	v_mul_f32_e32 v175, 0x4b800000, v0
	v_cmp_gt_f32_e32 vcc, s89, v0
	s_nop 1
	v_cndmask_b32_e32 v0, v0, v175, vcc
	v_rsq_f32_e32 v0, v0
	s_nop 0
	v_mul_f32_e32 v175, 0x45800000, v0
	v_cndmask_b32_e32 v0, v0, v175, vcc
	v_pk_mul_f32 v[192:193], v[102:103], v[0:1] op_sel_hi:[1,0]
	v_pk_mul_f32 v[194:195], v[104:105], v[0:1] op_sel_hi:[1,0]
	v_pk_mul_f32 v[200:201], v[98:99], v[0:1] op_sel_hi:[1,0]
	v_pk_mul_f32 v[198:199], v[100:101], v[0:1] op_sel_hi:[1,0]
	v_pk_mul_f32 v[194:195], v[136:137], v[194:195]
	v_pk_mul_f32 v[196:197], v[134:135], v[192:193]
	v_pk_mul_f32 v[198:199], v[132:133], v[198:199]
	s_and_b64 vcc, exec, s[6:7]
	v_pk_mul_f32 v[200:201], v[130:131], v[200:201]
	s_cbranch_vccnz .LBB0_338
	ds_bpermute_b32 v192, v212, v196
	ds_bpermute_b32 v193, v212, v197
	ds_bpermute_b32 v214, v212, v200
	ds_bpermute_b32 v216, v212, v194
	ds_bpermute_b32 v217, v212, v195
	ds_bpermute_b32 v215, v212, v201
	ds_bpermute_b32 v218, v212, v198
	ds_bpermute_b32 v219, v212, v199
	s_waitcnt lgkmcnt(6)
	v_pk_mul_f32 v[192:193], v[188:189], v[192:193]
	s_waitcnt lgkmcnt(3)
	v_pk_mul_f32 v[216:217], v[186:187], v[216:217]
	v_pk_fma_f32 v[196:197], v[142:143], v[196:197], v[192:193]
	s_waitcnt lgkmcnt(2)
	v_pk_mul_f32 v[192:193], v[182:183], v[214:215]
	s_waitcnt lgkmcnt(0)
	v_pk_mul_f32 v[214:215], v[184:185], v[218:219]
	v_pk_fma_f32 v[194:195], v[144:145], v[194:195], v[216:217]
	v_pk_fma_f32 v[198:199], v[140:141], v[198:199], v[214:215]
	v_pk_fma_f32 v[200:201], v[138:139], v[200:201], v[192:193]
.LBB0_338:
	v_ashrrev_i32_e32 v191, 31, v190
	v_lshlrev_b64 v[190:191], 8, v[190:191]
	v_lshl_add_u64 v[190:191], s[34:35], 0, v[190:191]
	v_mov_b32_e32 v192, v176
	v_mov_b32_e32 v193, v176
	v_lshl_add_u64 v[190:191], v[190:191], 0, s[50:51]
	v_pk_mul_f32 v[214:215], v[192:193], v[194:195]
	v_pk_mul_f32 v[194:195], v[176:177], v[196:197]
	v_pk_mul_f32 v[198:199], v[192:193], v[198:199]
	v_pk_mul_f32 v[196:197], v[176:177], v[200:201]
	v_lshl_add_u64 v[190:191], v[172:173], 1, v[190:191]
	v_cvt_pk_bf16_f32 v194, v194, v195
	v_cvt_pk_bf16_f32 v195, v214, v215
	v_cvt_pk_bf16_f32 v196, v196, v197
	v_cvt_pk_bf16_f32 v197, v198, v199
	global_store_dwordx4 v[190:191], v[194:197], off
	ds_read_b128 v[194:197], v213 offset:1040
	s_waitcnt lgkmcnt(0)
	v_mov_b32_e32 v198, v195
	v_mov_b32_e32 v199, v196
	v_mov_b32_e32 v195, v197
	v_pk_add_f32 v[194:195], v[198:199], v[194:195]
	s_nop 0
	v_add_f32_e32 v0, v194, v195
	v_fmamk_f32 v0, v0, 0x3c000000, v203
	v_cmp_gt_f32_e32 vcc, s89, v0
	v_mul_f32_e32 v175, 0x4b800000, v0
	s_nop 0
	v_cndmask_b32_e32 v0, v0, v175, vcc
	v_rsq_f32_e32 v0, v0
	s_nop 0
	v_mul_f32_e32 v175, 0x45800000, v0
	v_cndmask_b32_e32 v0, v0, v175, vcc
	v_pk_mul_f32 v[196:197], v[78:79], v[0:1] op_sel_hi:[1,0]
	v_pk_mul_f32 v[194:195], v[80:81], v[0:1] op_sel_hi:[1,0]
	v_pk_mul_f32 v[200:201], v[74:75], v[0:1] op_sel_hi:[1,0]
	v_pk_mul_f32 v[198:199], v[76:77], v[0:1] op_sel_hi:[1,0]
	v_pk_mul_f32 v[194:195], v[136:137], v[194:195]
	v_pk_mul_f32 v[196:197], v[134:135], v[196:197]
	v_pk_mul_f32 v[198:199], v[132:133], v[198:199]
	v_pk_mul_f32 v[200:201], v[130:131], v[200:201]
	s_and_b64 vcc, exec, s[6:7]
	s_cbranch_vccnz .LBB0_340
	ds_bpermute_b32 v214, v212, v196
	ds_bpermute_b32 v215, v212, v197
	ds_bpermute_b32 v218, v212, v194
	ds_bpermute_b32 v219, v212, v195
	ds_bpermute_b32 v216, v212, v200
	ds_bpermute_b32 v217, v212, v201
	ds_bpermute_b32 v220, v212, v198
	ds_bpermute_b32 v221, v212, v199
	s_waitcnt lgkmcnt(6)
	v_pk_mul_f32 v[188:189], v[188:189], v[214:215]
	s_waitcnt lgkmcnt(4)
	v_pk_mul_f32 v[186:187], v[186:187], v[218:219]
	v_pk_fma_f32 v[196:197], v[142:143], v[196:197], v[188:189]
	v_pk_fma_f32 v[194:195], v[144:145], v[194:195], v[186:187]
	s_waitcnt lgkmcnt(2)
	v_pk_mul_f32 v[142:143], v[182:183], v[216:217]
	s_waitcnt lgkmcnt(0)
	v_pk_mul_f32 v[144:145], v[184:185], v[220:221]
	v_pk_fma_f32 v[200:201], v[138:139], v[200:201], v[142:143]
	v_pk_fma_f32 v[198:199], v[140:141], v[198:199], v[144:145]
.LBB0_340:
	v_pk_mul_f32 v[140:141], v[192:193], v[194:195]
	v_pk_mul_f32 v[138:139], v[176:177], v[196:197]
	v_pk_mul_f32 v[142:143], v[192:193], v[198:199]
	v_cvt_pk_bf16_f32 v138, v138, v139
	v_cvt_pk_bf16_f32 v139, v140, v141
	v_cvt_pk_bf16_f32 v141, v142, v143
	v_add_co_u32_e32 v142, vcc, 0x800000, v190
	v_pk_mul_f32 v[144:145], v[176:177], v[200:201]
	s_nop 0
	v_addc_co_u32_e32 v143, vcc, 0, v191, vcc
	v_cvt_pk_bf16_f32 v140, v144, v145
	s_and_b64 vcc, exec, s[6:7]
	v_add_u32_e32 v190, 48, v174
	global_store_dwordx4 v[142:143], v[138:141], off
	s_cbranch_vccnz .LBB0_342
	s_waitcnt vmcnt(2)
	v_mov_b32_e32 v196, v178
	v_mov_b32_e32 v197, v178
	v_pk_mul_f32 v[186:187], v[196:197], v[224:225]
	v_pk_mul_f32 v[188:189], v[178:179], v[222:223]
	v_pk_mul_f32 v[184:185], v[196:197], v[228:229]
	v_pk_mul_f32 v[182:183], v[178:179], v[226:227]
	v_mov_b32_e32 v138, v230
	v_mov_b32_e32 v139, v231
	v_mov_b32_e32 v140, v232
	v_mov_b32_e32 v141, v233
	v_mov_b32_e32 v142, v234
	v_mov_b32_e32 v143, v235
	v_mov_b32_e32 v144, v236
	v_mov_b32_e32 v145, v237
	v_add_u32_e32 v0, 0x80, v174
	v_lshlrev_b32_e32 v0, 7, v0
	v_and_b32_e32 v0, 0xfff80, v0
	v_add_u32_e32 v0, v0, v180
	global_load_dwordx4 v[222:225], v0, s[18:19] offset:64
	global_load_dwordx4 v[226:229], v0, s[18:19] offset:80
	global_load_dwordx4 v[230:233], v0, s[18:19] offset:16
	global_load_dwordx4 v[234:237], v0, s[18:19]
	s_branch .LBB0_343

; #define LAS __attribute__((address_space(3)))
; __device__ __forceinline__ unsigned pk2(float lo, float hi) { f32x2 v = {lo, hi}; return __builtin_bit_cast(unsigned, __builtin_convertvector(v, bf16x2_t)); }
;     __device__ __forceinline__ void operator()(const f32x4 (&acc)[2][2][4][2], const Unit& u, int wr, int wc, int fr, int fq) const {
;     ...
;                 const int row = row0 + ai * HALF + m * 16;
;                 f32x4 cs[2] = {{1.f, 1.f, 1.f, 1.f}, {1.f, 1.f, 1.f, 1.f}}, sn[2] = {{0.f, 0.f, 0.f, 0.f}, {0.f, 0.f, 0.f, 0.f}};
;                 if (dorope) { const float* rp = rope + (size_t)(row & (SEQ - 1)) * 32 + 8 * (fq & 1);
;                     cs[0] = *(const f32x4*)rp; cs[1] = *(const f32x4*)(rp + 4); sn[0] = *(const f32x4*)(rp + 16); sn[1] = *(const f32x4*)(rp + 20);
;                     sn[0] = sn[0] * sgn; sn[1] = sn[1] * sgn; }
;                 bf16_t* rowp = O + ((size_t)(2 * u.pn) * MTOK + row) * 128 + wc * 32 + 8 * fq;
; #pragma unroll
;                 for (int bj = 0; bj < 2; ++bj) {
;                     const f32x4 t4 = *(const LAS f32x4*)(T + ((wr * 128 + ai * 64 + m * 16 + fr) * 2 + bj) * 4);
;                     const float rstd = rsqrtf(((t4[0] + t4[1]) + (t4[2] + t4[3])) * (1.0f / 128.0f) + EPSN);
;                     f32x4 v0 = acc[ai][bj][m][0] * rstd * gm[0], v1 = acc[ai][bj][m][1] * rstd * gm[1];
;                     if (dorope) {
;                         f32x4 p0, p1;
; #pragma unroll
;                         for (int e = 0; e < 4; ++e) { p0[e] = __shfl_xor(v0[e], 32); p1[e] = __shfl_xor(v1[e], 32); }
;                         v0 = v0 * cs[0] + p0 * sn[0]; v1 = v1 * cs[1] + p1 * sn[1];
;                     }
;                     v0 = v0 * mul; v1 = v1 * mul;
;                     u32x4 w; w.x = pk2(v0[0], v0[1]); w.y = pk2(v0[2], v0[3]); w.z = pk2(v1[0], v1[1]); w.w = pk2(v1[2], v1[3]);
;                     *(u32x4*)(rowp + (size_t)bj * MTOK * 128) = w;
.LBB0_343:
	ds_read_b128 v[192:195], v213 offset:1536
	s_waitcnt lgkmcnt(0)
	v_mov_b32_e32 v196, v193
	v_mov_b32_e32 v197, v194
	v_mov_b32_e32 v193, v195
	v_pk_add_f32 v[192:193], v[196:197], v[192:193]
	s_nop 0
	v_add_f32_e32 v0, v192, v193
	v_fmamk_f32 v0, v0, 0x3c000000, v203
	v_mul_f32_e32 v175, 0x4b800000, v0
	v_cmp_gt_f32_e32 vcc, s89, v0
	s_nop 1
	v_cndmask_b32_e32 v0, v0, v175, vcc
	v_rsq_f32_e32 v0, v0
	s_nop 0
	v_mul_f32_e32 v175, 0x45800000, v0
	v_cndmask_b32_e32 v0, v0, v175, vcc
	v_pk_mul_f32 v[192:193], v[86:87], v[0:1] op_sel_hi:[1,0]
	v_pk_mul_f32 v[194:195], v[88:89], v[0:1] op_sel_hi:[1,0]
	v_pk_mul_f32 v[200:201], v[82:83], v[0:1] op_sel_hi:[1,0]
	v_pk_mul_f32 v[198:199], v[84:85], v[0:1] op_sel_hi:[1,0]
	v_pk_mul_f32 v[194:195], v[136:137], v[194:195]
	v_pk_mul_f32 v[196:197], v[134:135], v[192:193]
	v_pk_mul_f32 v[198:199], v[132:133], v[198:199]
	s_and_b64 vcc, exec, s[6:7]
	v_pk_mul_f32 v[200:201], v[130:131], v[200:201]
	s_cbranch_vccnz .LBB0_345
	ds_bpermute_b32 v192, v212, v196
	ds_bpermute_b32 v193, v212, v197
	ds_bpermute_b32 v214, v212, v200
	ds_bpermute_b32 v216, v212, v194
	ds_bpermute_b32 v217, v212, v195
	ds_bpermute_b32 v215, v212, v201
	ds_bpermute_b32 v218, v212, v198
	ds_bpermute_b32 v219, v212, v199
	s_waitcnt lgkmcnt(6)
	v_pk_mul_f32 v[192:193], v[188:189], v[192:193]
	s_waitcnt lgkmcnt(3)
	v_pk_mul_f32 v[216:217], v[186:187], v[216:217]
	v_pk_fma_f32 v[196:197], v[142:143], v[196:197], v[192:193]
	s_waitcnt lgkmcnt(2)
	v_pk_mul_f32 v[192:193], v[182:183], v[214:215]
	s_waitcnt lgkmcnt(0)
	v_pk_mul_f32 v[214:215], v[184:185], v[218:219]
	v_pk_fma_f32 v[194:195], v[144:145], v[194:195], v[216:217]
	v_pk_fma_f32 v[198:199], v[140:141], v[198:199], v[214:215]
	v_pk_fma_f32 v[200:201], v[138:139], v[200:201], v[192:193]
.LBB0_345:
	v_ashrrev_i32_e32 v191, 31, v190
	v_lshlrev_b64 v[190:191], 8, v[190:191]
	v_lshl_add_u64 v[190:191], s[34:35], 0, v[190:191]
	v_mov_b32_e32 v192, v176
	v_mov_b32_e32 v193, v176
	v_lshl_add_u64 v[190:191], v[190:191], 0, s[50:51]
	v_pk_mul_f32 v[214:215], v[192:193], v[194:195]
	v_pk_mul_f32 v[194:195], v[176:177], v[196:197]
	v_pk_mul_f32 v[198:199], v[192:193], v[198:199]
	v_pk_mul_f32 v[196:197], v[176:177], v[200:201]
	v_lshl_add_u64 v[190:191], v[172:173], 1, v[190:191]
	v_cvt_pk_bf16_f32 v194, v194, v195
	v_cvt_pk_bf16_f32 v195, v214, v215
	v_cvt_pk_bf16_f32 v196, v196, v197
	v_cvt_pk_bf16_f32 v197, v198, v199
	global_store_dwordx4 v[190:191], v[194:197], off
	ds_read_b128 v[194:197], v213 offset:1552
	s_waitcnt lgkmcnt(0)
	v_mov_b32_e32 v198, v195
	v_mov_b32_e32 v199, v196
	v_mov_b32_e32 v195, v197
	v_pk_add_f32 v[194:195], v[198:199], v[194:195]
	s_nop 0
	v_add_f32_e32 v0, v194, v195
	v_fmamk_f32 v0, v0, 0x3c000000, v203
	v_cmp_gt_f32_e32 vcc, s89, v0
	v_mul_f32_e32 v175, 0x4b800000, v0
	s_nop 0
	v_cndmask_b32_e32 v0, v0, v175, vcc
	v_rsq_f32_e32 v0, v0
	s_nop 0
	v_mul_f32_e32 v175, 0x45800000, v0
	v_cndmask_b32_e32 v0, v0, v175, vcc
	v_pk_mul_f32 v[196:197], v[70:71], v[0:1] op_sel_hi:[1,0]
	v_pk_mul_f32 v[194:195], v[72:73], v[0:1] op_sel_hi:[1,0]
	v_pk_mul_f32 v[200:201], v[66:67], v[0:1] op_sel_hi:[1,0]
	v_pk_mul_f32 v[198:199], v[68:69], v[0:1] op_sel_hi:[1,0]
	v_pk_mul_f32 v[194:195], v[136:137], v[194:195]
	v_pk_mul_f32 v[196:197], v[134:135], v[196:197]
	v_pk_mul_f32 v[198:199], v[132:133], v[198:199]
	v_pk_mul_f32 v[200:201], v[130:131], v[200:201]
	s_and_b64 vcc, exec, s[6:7]
	s_cbranch_vccnz .LBB0_347
	ds_bpermute_b32 v214, v212, v196
	ds_bpermute_b32 v215, v212, v197
	ds_bpermute_b32 v218, v212, v194
	ds_bpermute_b32 v219, v212, v195
	ds_bpermute_b32 v216, v212, v200
	ds_bpermute_b32 v217, v212, v201
	ds_bpermute_b32 v220, v212, v198
	ds_bpermute_b32 v221, v212, v199
	s_waitcnt lgkmcnt(6)
	v_pk_mul_f32 v[188:189], v[188:189], v[214:215]
	s_waitcnt lgkmcnt(4)
	v_pk_mul_f32 v[186:187], v[186:187], v[218:219]
	v_pk_fma_f32 v[196:197], v[142:143], v[196:197], v[188:189]
	v_pk_fma_f32 v[194:195], v[144:145], v[194:195], v[186:187]
	s_waitcnt lgkmcnt(2)
	v_pk_mul_f32 v[142:143], v[182:183], v[216:217]
	s_waitcnt lgkmcnt(0)
	v_pk_mul_f32 v[144:145], v[184:185], v[220:221]
	v_pk_fma_f32 v[200:201], v[138:139], v[200:201], v[142:143]
	v_pk_fma_f32 v[198:199], v[140:141], v[198:199], v[144:145]
.LBB0_347:
	v_pk_mul_f32 v[140:141], v[192:193], v[194:195]
	v_pk_mul_f32 v[138:139], v[176:177], v[196:197]
	v_pk_mul_f32 v[142:143], v[192:193], v[198:199]
	v_cvt_pk_bf16_f32 v138, v138, v139
	v_cvt_pk_bf16_f32 v139, v140, v141
	v_cvt_pk_bf16_f32 v141, v142, v143
	v_add_co_u32_e32 v142, vcc, 0x800000, v190
	v_pk_mul_f32 v[144:145], v[176:177], v[200:201]
	s_nop 0
	v_addc_co_u32_e32 v143, vcc, 0, v191, vcc
	v_cvt_pk_bf16_f32 v140, v144, v145
	s_and_b64 vcc, exec, s[6:7]
	v_add_u32_e32 v190, 0x80, v174
	global_store_dwordx4 v[142:143], v[138:141], off
	s_cbranch_vccnz .LBB0_349
	s_waitcnt vmcnt(2)
	v_mov_b32_e32 v196, v178
	v_mov_b32_e32 v197, v178
	v_pk_mul_f32 v[186:187], v[196:197], v[224:225]
	v_pk_mul_f32 v[188:189], v[178:179], v[222:223]
	v_pk_mul_f32 v[184:185], v[196:197], v[228:229]
	v_pk_mul_f32 v[182:183], v[178:179], v[226:227]
	v_mov_b32_e32 v138, v230
	v_mov_b32_e32 v139, v231
	v_mov_b32_e32 v140, v232
	v_mov_b32_e32 v141, v233
	v_mov_b32_e32 v142, v234
	v_mov_b32_e32 v143, v235
	v_mov_b32_e32 v144, v236
	v_mov_b32_e32 v145, v237
	v_add_u32_e32 v0, 0x90, v174
	v_lshlrev_b32_e32 v0, 7, v0
	v_and_b32_e32 v0, 0xfff80, v0
	v_add_u32_e32 v0, v0, v180
	global_load_dwordx4 v[222:225], v0, s[18:19] offset:64
	global_load_dwordx4 v[226:229], v0, s[18:19] offset:80
	global_load_dwordx4 v[230:233], v0, s[18:19] offset:16
	global_load_dwordx4 v[234:237], v0, s[18:19]
	s_branch .LBB0_350

; #define LAS __attribute__((address_space(3)))
; __device__ __forceinline__ unsigned pk2(float lo, float hi) { f32x2 v = {lo, hi}; return __builtin_bit_cast(unsigned, __builtin_convertvector(v, bf16x2_t)); }
;     __device__ __forceinline__ void operator()(const f32x4 (&acc)[2][2][4][2], const Unit& u, int wr, int wc, int fr, int fq) const {
;     ...
;                 const int row = row0 + ai * HALF + m * 16;
;                 f32x4 cs[2] = {{1.f, 1.f, 1.f, 1.f}, {1.f, 1.f, 1.f, 1.f}}, sn[2] = {{0.f, 0.f, 0.f, 0.f}, {0.f, 0.f, 0.f, 0.f}};
;                 if (dorope) { const float* rp = rope + (size_t)(row & (SEQ - 1)) * 32 + 8 * (fq & 1);
;                     cs[0] = *(const f32x4*)rp; cs[1] = *(const f32x4*)(rp + 4); sn[0] = *(const f32x4*)(rp + 16); sn[1] = *(const f32x4*)(rp + 20);
;                     sn[0] = sn[0] * sgn; sn[1] = sn[1] * sgn; }
;                 bf16_t* rowp = O + ((size_t)(2 * u.pn) * MTOK + row) * 128 + wc * 32 + 8 * fq;
; #pragma unroll
;                 for (int bj = 0; bj < 2; ++bj) {
;                     const f32x4 t4 = *(const LAS f32x4*)(T + ((wr * 128 + ai * 64 + m * 16 + fr) * 2 + bj) * 4);
;                     const float rstd = rsqrtf(((t4[0] + t4[1]) + (t4[2] + t4[3])) * (1.0f / 128.0f) + EPSN);
;                     f32x4 v0 = acc[ai][bj][m][0] * rstd * gm[0], v1 = acc[ai][bj][m][1] * rstd * gm[1];
;                     if (dorope) {
;                         f32x4 p0, p1;
; #pragma unroll
;                         for (int e = 0; e < 4; ++e) { p0[e] = __shfl_xor(v0[e], 32); p1[e] = __shfl_xor(v1[e], 32); }
;                         v0 = v0 * cs[0] + p0 * sn[0]; v1 = v1 * cs[1] + p1 * sn[1];
;                     }
;                     v0 = v0 * mul; v1 = v1 * mul;
;                     u32x4 w; w.x = pk2(v0[0], v0[1]); w.y = pk2(v0[2], v0[3]); w.z = pk2(v1[0], v1[1]); w.w = pk2(v1[2], v1[3]);
;                     *(u32x4*)(rowp + (size_t)bj * MTOK * 128) = w;
.LBB0_350:
	ds_read_b128 v[192:195], v213 offset:2048
	s_waitcnt lgkmcnt(0)
	v_mov_b32_e32 v196, v193
	v_mov_b32_e32 v197, v194
	v_mov_b32_e32 v193, v195
	v_pk_add_f32 v[192:193], v[196:197], v[192:193]
	s_nop 0
	v_add_f32_e32 v0, v192, v193
	v_fmamk_f32 v0, v0, 0x3c000000, v203
	v_mul_f32_e32 v175, 0x4b800000, v0
	v_cmp_gt_f32_e32 vcc, s89, v0
	s_nop 1
	v_cndmask_b32_e32 v0, v0, v175, vcc
	v_rsq_f32_e32 v0, v0
	s_nop 0
	v_mul_f32_e32 v175, 0x45800000, v0
	v_cndmask_b32_e32 v0, v0, v175, vcc
	v_pk_mul_f32 v[192:193], v[62:63], v[0:1] op_sel_hi:[1,0]
	v_pk_mul_f32 v[194:195], v[64:65], v[0:1] op_sel_hi:[1,0]
	v_pk_mul_f32 v[200:201], v[58:59], v[0:1] op_sel_hi:[1,0]
	v_pk_mul_f32 v[198:199], v[60:61], v[0:1] op_sel_hi:[1,0]
	v_pk_mul_f32 v[194:195], v[136:137], v[194:195]
	v_pk_mul_f32 v[196:197], v[134:135], v[192:193]
	v_pk_mul_f32 v[198:199], v[132:133], v[198:199]
	s_and_b64 vcc, exec, s[6:7]
	v_pk_mul_f32 v[200:201], v[130:131], v[200:201]
	s_cbranch_vccnz .LBB0_352
	ds_bpermute_b32 v192, v212, v196
	ds_bpermute_b32 v193, v212, v197
	ds_bpermute_b32 v214, v212, v200
	ds_bpermute_b32 v216, v212, v194
	ds_bpermute_b32 v217, v212, v195
	ds_bpermute_b32 v215, v212, v201
	ds_bpermute_b32 v218, v212, v198
	ds_bpermute_b32 v219, v212, v199
	s_waitcnt lgkmcnt(6)
	v_pk_mul_f32 v[192:193], v[188:189], v[192:193]
	s_waitcnt lgkmcnt(3)
	v_pk_mul_f32 v[216:217], v[186:187], v[216:217]
	v_pk_fma_f32 v[196:197], v[142:143], v[196:197], v[192:193]
	s_waitcnt lgkmcnt(2)
	v_pk_mul_f32 v[192:193], v[182:183], v[214:215]
	s_waitcnt lgkmcnt(0)
	v_pk_mul_f32 v[214:215], v[184:185], v[218:219]
	v_pk_fma_f32 v[194:195], v[144:145], v[194:195], v[216:217]
	v_pk_fma_f32 v[198:199], v[140:141], v[198:199], v[214:215]
	v_pk_fma_f32 v[200:201], v[138:139], v[200:201], v[192:193]
.LBB0_352:
	v_ashrrev_i32_e32 v191, 31, v190
	v_lshlrev_b64 v[190:191], 8, v[190:191]
	v_lshl_add_u64 v[190:191], s[34:35], 0, v[190:191]
	v_mov_b32_e32 v192, v176
	v_mov_b32_e32 v193, v176
	v_lshl_add_u64 v[190:191], v[190:191], 0, s[50:51]
	v_pk_mul_f32 v[214:215], v[192:193], v[194:195]
	v_pk_mul_f32 v[194:195], v[176:177], v[196:197]
	v_pk_mul_f32 v[198:199], v[192:193], v[198:199]
	v_pk_mul_f32 v[196:197], v[176:177], v[200:201]
	v_lshl_add_u64 v[190:191], v[172:173], 1, v[190:191]
	v_cvt_pk_bf16_f32 v194, v194, v195
	v_cvt_pk_bf16_f32 v195, v214, v215
	v_cvt_pk_bf16_f32 v196, v196, v197
	v_cvt_pk_bf16_f32 v197, v198, v199
	global_store_dwordx4 v[190:191], v[194:197], off
	ds_read_b128 v[194:197], v213 offset:2064
	s_waitcnt lgkmcnt(0)
	v_mov_b32_e32 v198, v195
	v_mov_b32_e32 v199, v196
	v_mov_b32_e32 v195, v197
	v_pk_add_f32 v[194:195], v[198:199], v[194:195]
	s_nop 0
	v_add_f32_e32 v0, v194, v195
	v_fmamk_f32 v0, v0, 0x3c000000, v203
	v_cmp_gt_f32_e32 vcc, s89, v0
	v_mul_f32_e32 v175, 0x4b800000, v0
	s_nop 0
	v_cndmask_b32_e32 v0, v0, v175, vcc
	v_rsq_f32_e32 v0, v0
	s_nop 0
	v_mul_f32_e32 v175, 0x45800000, v0
	v_cndmask_b32_e32 v0, v0, v175, vcc
	v_pk_mul_f32 v[196:197], v[46:47], v[0:1] op_sel_hi:[1,0]
	v_pk_mul_f32 v[194:195], v[48:49], v[0:1] op_sel_hi:[1,0]
	v_pk_mul_f32 v[200:201], v[42:43], v[0:1] op_sel_hi:[1,0]
	v_pk_mul_f32 v[198:199], v[44:45], v[0:1] op_sel_hi:[1,0]
	v_pk_mul_f32 v[194:195], v[136:137], v[194:195]
	v_pk_mul_f32 v[196:197], v[134:135], v[196:197]
	v_pk_mul_f32 v[198:199], v[132:133], v[198:199]
	v_pk_mul_f32 v[200:201], v[130:131], v[200:201]
	s_and_b64 vcc, exec, s[6:7]
	s_cbranch_vccnz .LBB0_354
	ds_bpermute_b32 v214, v212, v196
	ds_bpermute_b32 v215, v212, v197
	ds_bpermute_b32 v218, v212, v194
	ds_bpermute_b32 v219, v212, v195
	ds_bpermute_b32 v216, v212, v200
	ds_bpermute_b32 v217, v212, v201
	ds_bpermute_b32 v220, v212, v198
	ds_bpermute_b32 v221, v212, v199
	s_waitcnt lgkmcnt(6)
	v_pk_mul_f32 v[188:189], v[188:189], v[214:215]
	s_waitcnt lgkmcnt(4)
	v_pk_mul_f32 v[186:187], v[186:187], v[218:219]
	v_pk_fma_f32 v[196:197], v[142:143], v[196:197], v[188:189]
	v_pk_fma_f32 v[194:195], v[144:145], v[194:195], v[186:187]
	s_waitcnt lgkmcnt(2)
	v_pk_mul_f32 v[142:143], v[182:183], v[216:217]
	s_waitcnt lgkmcnt(0)
	v_pk_mul_f32 v[144:145], v[184:185], v[220:221]
	v_pk_fma_f32 v[200:201], v[138:139], v[200:201], v[142:143]
	v_pk_fma_f32 v[198:199], v[140:141], v[198:199], v[144:145]
.LBB0_354:
	v_pk_mul_f32 v[140:141], v[192:193], v[194:195]
	v_pk_mul_f32 v[138:139], v[176:177], v[196:197]
	v_pk_mul_f32 v[142:143], v[192:193], v[198:199]
	v_cvt_pk_bf16_f32 v138, v138, v139
	v_cvt_pk_bf16_f32 v139, v140, v141
	v_cvt_pk_bf16_f32 v141, v142, v143
	v_add_co_u32_e32 v142, vcc, 0x800000, v190
	v_pk_mul_f32 v[144:145], v[176:177], v[200:201]
	s_nop 0
	v_addc_co_u32_e32 v143, vcc, 0, v191, vcc
	v_cvt_pk_bf16_f32 v140, v144, v145
	s_and_b64 vcc, exec, s[6:7]
	v_add_u32_e32 v190, 0x90, v174
	global_store_dwordx4 v[142:143], v[138:141], off
	s_cbranch_vccnz .LBB0_356
	s_waitcnt vmcnt(2)
	v_mov_b32_e32 v196, v178
	v_mov_b32_e32 v197, v178
	v_pk_mul_f32 v[186:187], v[196:197], v[224:225]
	v_pk_mul_f32 v[188:189], v[178:179], v[222:223]
	v_pk_mul_f32 v[184:185], v[196:197], v[228:229]
	v_pk_mul_f32 v[182:183], v[178:179], v[226:227]
	v_mov_b32_e32 v138, v230
	v_mov_b32_e32 v139, v231
	v_mov_b32_e32 v140, v232
	v_mov_b32_e32 v141, v233
	v_mov_b32_e32 v142, v234
	v_mov_b32_e32 v143, v235
	v_mov_b32_e32 v144, v236
	v_mov_b32_e32 v145, v237
	v_add_u32_e32 v0, 0xa0, v174
	v_lshlrev_b32_e32 v0, 7, v0
	v_and_b32_e32 v0, 0xfff80, v0
	v_add_u32_e32 v0, v0, v180
	global_load_dwordx4 v[222:225], v0, s[18:19] offset:64
	global_load_dwordx4 v[226:229], v0, s[18:19] offset:80
	global_load_dwordx4 v[230:233], v0, s[18:19] offset:16
	global_load_dwordx4 v[234:237], v0, s[18:19]
	s_branch .LBB0_357

; #define LAS __attribute__((address_space(3)))
; __device__ __forceinline__ unsigned pk2(float lo, float hi) { f32x2 v = {lo, hi}; return __builtin_bit_cast(unsigned, __builtin_convertvector(v, bf16x2_t)); }
;     __device__ __forceinline__ void operator()(const f32x4 (&acc)[2][2][4][2], const Unit& u, int wr, int wc, int fr, int fq) const {
;     ...
;                 const int row = row0 + ai * HALF + m * 16;
;                 f32x4 cs[2] = {{1.f, 1.f, 1.f, 1.f}, {1.f, 1.f, 1.f, 1.f}}, sn[2] = {{0.f, 0.f, 0.f, 0.f}, {0.f, 0.f, 0.f, 0.f}};
;                 if (dorope) { const float* rp = rope + (size_t)(row & (SEQ - 1)) * 32 + 8 * (fq & 1);
;                     cs[0] = *(const f32x4*)rp; cs[1] = *(const f32x4*)(rp + 4); sn[0] = *(const f32x4*)(rp + 16); sn[1] = *(const f32x4*)(rp + 20);
;                     sn[0] = sn[0] * sgn; sn[1] = sn[1] * sgn; }
;                 bf16_t* rowp = O + ((size_t)(2 * u.pn) * MTOK + row) * 128 + wc * 32 + 8 * fq;
; #pragma unroll
;                 for (int bj = 0; bj < 2; ++bj) {
;                     const f32x4 t4 = *(const LAS f32x4*)(T + ((wr * 128 + ai * 64 + m * 16 + fr) * 2 + bj) * 4);
;                     const float rstd = rsqrtf(((t4[0] + t4[1]) + (t4[2] + t4[3])) * (1.0f / 128.0f) + EPSN);
;                     f32x4 v0 = acc[ai][bj][m][0] * rstd * gm[0], v1 = acc[ai][bj][m][1] * rstd * gm[1];
;                     if (dorope) {
;                         f32x4 p0, p1;
; #pragma unroll
;                         for (int e = 0; e < 4; ++e) { p0[e] = __shfl_xor(v0[e], 32); p1[e] = __shfl_xor(v1[e], 32); }
;                         v0 = v0 * cs[0] + p0 * sn[0]; v1 = v1 * cs[1] + p1 * sn[1];
;                     }
;                     v0 = v0 * mul; v1 = v1 * mul;
;                     u32x4 w; w.x = pk2(v0[0], v0[1]); w.y = pk2(v0[2], v0[3]); w.z = pk2(v1[0], v1[1]); w.w = pk2(v1[2], v1[3]);
;                     *(u32x4*)(rowp + (size_t)bj * MTOK * 128) = w;
.LBB0_357:
	ds_read_b128 v[192:195], v213 offset:2560
	s_waitcnt lgkmcnt(0)
	v_mov_b32_e32 v196, v193
	v_mov_b32_e32 v197, v194
	v_mov_b32_e32 v193, v195
	v_pk_add_f32 v[192:193], v[196:197], v[192:193]
	s_nop 0
	v_add_f32_e32 v0, v192, v193
	v_fmamk_f32 v0, v0, 0x3c000000, v203
	v_mul_f32_e32 v175, 0x4b800000, v0
	v_cmp_gt_f32_e32 vcc, s89, v0
	s_nop 1
	v_cndmask_b32_e32 v0, v0, v175, vcc
	v_rsq_f32_e32 v0, v0
	s_nop 0
	v_mul_f32_e32 v175, 0x45800000, v0
	v_cndmask_b32_e32 v0, v0, v175, vcc
	v_pk_mul_f32 v[192:193], v[54:55], v[0:1] op_sel_hi:[1,0]
	v_pk_mul_f32 v[194:195], v[56:57], v[0:1] op_sel_hi:[1,0]
	v_pk_mul_f32 v[200:201], v[50:51], v[0:1] op_sel_hi:[1,0]
	v_pk_mul_f32 v[198:199], v[52:53], v[0:1] op_sel_hi:[1,0]
	v_pk_mul_f32 v[194:195], v[136:137], v[194:195]
	v_pk_mul_f32 v[196:197], v[134:135], v[192:193]
	v_pk_mul_f32 v[198:199], v[132:133], v[198:199]
	s_and_b64 vcc, exec, s[6:7]
	v_pk_mul_f32 v[200:201], v[130:131], v[200:201]
	s_cbranch_vccnz .LBB0_359
	ds_bpermute_b32 v192, v212, v196
	ds_bpermute_b32 v193, v212, v197
	ds_bpermute_b32 v214, v212, v200
	ds_bpermute_b32 v216, v212, v194
	ds_bpermute_b32 v217, v212, v195
	ds_bpermute_b32 v215, v212, v201
	ds_bpermute_b32 v218, v212, v198
	ds_bpermute_b32 v219, v212, v199
	s_waitcnt lgkmcnt(6)
	v_pk_mul_f32 v[192:193], v[188:189], v[192:193]
	s_waitcnt lgkmcnt(3)
	v_pk_mul_f32 v[216:217], v[186:187], v[216:217]
	v_pk_fma_f32 v[196:197], v[142:143], v[196:197], v[192:193]
	s_waitcnt lgkmcnt(2)
	v_pk_mul_f32 v[192:193], v[182:183], v[214:215]
	s_waitcnt lgkmcnt(0)
	v_pk_mul_f32 v[214:215], v[184:185], v[218:219]
	v_pk_fma_f32 v[194:195], v[144:145], v[194:195], v[216:217]
	v_pk_fma_f32 v[198:199], v[140:141], v[198:199], v[214:215]
	v_pk_fma_f32 v[200:201], v[138:139], v[200:201], v[192:193]
.LBB0_359:
	v_ashrrev_i32_e32 v191, 31, v190
	v_lshlrev_b64 v[190:191], 8, v[190:191]
	v_lshl_add_u64 v[190:191], s[34:35], 0, v[190:191]
	v_mov_b32_e32 v192, v176
	v_mov_b32_e32 v193, v176
	v_lshl_add_u64 v[190:191], v[190:191], 0, s[50:51]
	v_pk_mul_f32 v[214:215], v[192:193], v[194:195]
	v_pk_mul_f32 v[194:195], v[176:177], v[196:197]
	v_pk_mul_f32 v[198:199], v[192:193], v[198:199]
	v_pk_mul_f32 v[196:197], v[176:177], v[200:201]
	v_lshl_add_u64 v[190:191], v[172:173], 1, v[190:191]
	v_cvt_pk_bf16_f32 v194, v194, v195
	v_cvt_pk_bf16_f32 v195, v214, v215
	v_cvt_pk_bf16_f32 v196, v196, v197
	v_cvt_pk_bf16_f32 v197, v198, v199
	global_store_dwordx4 v[190:191], v[194:197], off
	ds_read_b128 v[194:197], v213 offset:2576
	s_waitcnt lgkmcnt(0)
	v_mov_b32_e32 v198, v195
	v_mov_b32_e32 v199, v196
	v_mov_b32_e32 v195, v197
	v_pk_add_f32 v[194:195], v[198:199], v[194:195]
	s_nop 0
	v_add_f32_e32 v0, v194, v195
	v_fmamk_f32 v0, v0, 0x3c000000, v203
	v_cmp_gt_f32_e32 vcc, s89, v0
	v_mul_f32_e32 v175, 0x4b800000, v0
	s_nop 0
	v_cndmask_b32_e32 v0, v0, v175, vcc
	v_rsq_f32_e32 v0, v0
	s_nop 0
	v_mul_f32_e32 v175, 0x45800000, v0
	v_cndmask_b32_e32 v0, v0, v175, vcc
	v_pk_mul_f32 v[196:197], v[30:31], v[0:1] op_sel_hi:[1,0]
	v_pk_mul_f32 v[194:195], v[32:33], v[0:1] op_sel_hi:[1,0]
	v_pk_mul_f32 v[200:201], v[26:27], v[0:1] op_sel_hi:[1,0]
	v_pk_mul_f32 v[198:199], v[28:29], v[0:1] op_sel_hi:[1,0]
	v_pk_mul_f32 v[194:195], v[136:137], v[194:195]
	v_pk_mul_f32 v[196:197], v[134:135], v[196:197]
	v_pk_mul_f32 v[198:199], v[132:133], v[198:199]
	v_pk_mul_f32 v[200:201], v[130:131], v[200:201]
	s_and_b64 vcc, exec, s[6:7]
	s_cbranch_vccnz .LBB0_361
	ds_bpermute_b32 v214, v212, v196
	ds_bpermute_b32 v215, v212, v197
	ds_bpermute_b32 v218, v212, v194
	ds_bpermute_b32 v219, v212, v195
	ds_bpermute_b32 v216, v212, v200
	ds_bpermute_b32 v217, v212, v201
	ds_bpermute_b32 v220, v212, v198
	ds_bpermute_b32 v221, v212, v199
	s_waitcnt lgkmcnt(6)
	v_pk_mul_f32 v[188:189], v[188:189], v[214:215]
	s_waitcnt lgkmcnt(4)
	v_pk_mul_f32 v[186:187], v[186:187], v[218:219]
	v_pk_fma_f32 v[196:197], v[142:143], v[196:197], v[188:189]
	v_pk_fma_f32 v[194:195], v[144:145], v[194:195], v[186:187]
	s_waitcnt lgkmcnt(2)
	v_pk_mul_f32 v[142:143], v[182:183], v[216:217]
	s_waitcnt lgkmcnt(0)
	v_pk_mul_f32 v[144:145], v[184:185], v[220:221]
	v_pk_fma_f32 v[200:201], v[138:139], v[200:201], v[142:143]
	v_pk_fma_f32 v[198:199], v[140:141], v[198:199], v[144:145]
.LBB0_361:
	v_pk_mul_f32 v[140:141], v[192:193], v[194:195]
	v_pk_mul_f32 v[138:139], v[176:177], v[196:197]
	v_pk_mul_f32 v[142:143], v[192:193], v[198:199]
	v_cvt_pk_bf16_f32 v138, v138, v139
	v_cvt_pk_bf16_f32 v139, v140, v141
	v_cvt_pk_bf16_f32 v141, v142, v143
	v_add_co_u32_e32 v142, vcc, 0x800000, v190
	v_pk_mul_f32 v[144:145], v[176:177], v[200:201]
	s_nop 0
	v_addc_co_u32_e32 v143, vcc, 0, v191, vcc
	v_cvt_pk_bf16_f32 v140, v144, v145
	s_and_b64 vcc, exec, s[6:7]
	v_add_u32_e32 v190, 0xa0, v174
	global_store_dwordx4 v[142:143], v[138:141], off
	s_cbranch_vccnz .LBB0_363
	s_waitcnt vmcnt(2)
	v_mov_b32_e32 v196, v178
	v_mov_b32_e32 v197, v178
	v_pk_mul_f32 v[186:187], v[196:197], v[224:225]
	v_pk_mul_f32 v[188:189], v[178:179], v[222:223]
	v_pk_mul_f32 v[184:185], v[196:197], v[228:229]
	v_pk_mul_f32 v[182:183], v[178:179], v[226:227]
	v_mov_b32_e32 v138, v230
	v_mov_b32_e32 v139, v231
	v_mov_b32_e32 v140, v232
	v_mov_b32_e32 v141, v233
	v_mov_b32_e32 v142, v234
	v_mov_b32_e32 v143, v235
	v_mov_b32_e32 v144, v236
	v_mov_b32_e32 v145, v237
	v_add_u32_e32 v0, 0xb0, v174
	v_lshlrev_b32_e32 v0, 7, v0
	v_and_b32_e32 v0, 0xfff80, v0
	v_add_u32_e32 v0, v0, v180
	global_load_dwordx4 v[222:225], v0, s[18:19] offset:64
	global_load_dwordx4 v[226:229], v0, s[18:19] offset:80
	global_load_dwordx4 v[230:233], v0, s[18:19] offset:16
	global_load_dwordx4 v[234:237], v0, s[18:19]
	s_branch .LBB0_364

; #define LAS __attribute__((address_space(3)))
; __device__ __forceinline__ unsigned pk2(float lo, float hi) { f32x2 v = {lo, hi}; return __builtin_bit_cast(unsigned, __builtin_convertvector(v, bf16x2_t)); }
;     __device__ __forceinline__ void operator()(const f32x4 (&acc)[2][2][4][2], const Unit& u, int wr, int wc, int fr, int fq) const {
;     ...
;                 const int row = row0 + ai * HALF + m * 16;
;                 f32x4 cs[2] = {{1.f, 1.f, 1.f, 1.f}, {1.f, 1.f, 1.f, 1.f}}, sn[2] = {{0.f, 0.f, 0.f, 0.f}, {0.f, 0.f, 0.f, 0.f}};
;                 if (dorope) { const float* rp = rope + (size_t)(row & (SEQ - 1)) * 32 + 8 * (fq & 1);
;                     cs[0] = *(const f32x4*)rp; cs[1] = *(const f32x4*)(rp + 4); sn[0] = *(const f32x4*)(rp + 16); sn[1] = *(const f32x4*)(rp + 20);
;                     sn[0] = sn[0] * sgn; sn[1] = sn[1] * sgn; }
;                 bf16_t* rowp = O + ((size_t)(2 * u.pn) * MTOK + row) * 128 + wc * 32 + 8 * fq;
; #pragma unroll
;                 for (int bj = 0; bj < 2; ++bj) {
;                     const f32x4 t4 = *(const LAS f32x4*)(T + ((wr * 128 + ai * 64 + m * 16 + fr) * 2 + bj) * 4);
;                     const float rstd = rsqrtf(((t4[0] + t4[1]) + (t4[2] + t4[3])) * (1.0f / 128.0f) + EPSN);
;                     f32x4 v0 = acc[ai][bj][m][0] * rstd * gm[0], v1 = acc[ai][bj][m][1] * rstd * gm[1];
;                     if (dorope) {
;                         f32x4 p0, p1;
; #pragma unroll
;                         for (int e = 0; e < 4; ++e) { p0[e] = __shfl_xor(v0[e], 32); p1[e] = __shfl_xor(v1[e], 32); }
;                         v0 = v0 * cs[0] + p0 * sn[0]; v1 = v1 * cs[1] + p1 * sn[1];
;                     }
;                     v0 = v0 * mul; v1 = v1 * mul;
;                     u32x4 w; w.x = pk2(v0[0], v0[1]); w.y = pk2(v0[2], v0[3]); w.z = pk2(v1[0], v1[1]); w.w = pk2(v1[2], v1[3]);
;                     *(u32x4*)(rowp + (size_t)bj * MTOK * 128) = w;
.LBB0_364:
	ds_read_b128 v[192:195], v213 offset:3072
	s_waitcnt lgkmcnt(0)
	v_mov_b32_e32 v196, v193
	v_mov_b32_e32 v197, v194
	v_mov_b32_e32 v193, v195
	v_pk_add_f32 v[192:193], v[196:197], v[192:193]
	s_nop 0
	v_add_f32_e32 v0, v192, v193
	v_fmamk_f32 v0, v0, 0x3c000000, v203
	v_mul_f32_e32 v175, 0x4b800000, v0
	v_cmp_gt_f32_e32 vcc, s89, v0
	s_nop 1
	v_cndmask_b32_e32 v0, v0, v175, vcc
	v_rsq_f32_e32 v0, v0
	s_nop 0
	v_mul_f32_e32 v175, 0x45800000, v0
	v_cndmask_b32_e32 v0, v0, v175, vcc
	v_pk_mul_f32 v[192:193], v[38:39], v[0:1] op_sel_hi:[1,0]
	v_pk_mul_f32 v[194:195], v[40:41], v[0:1] op_sel_hi:[1,0]
	v_pk_mul_f32 v[200:201], v[34:35], v[0:1] op_sel_hi:[1,0]
	v_pk_mul_f32 v[198:199], v[36:37], v[0:1] op_sel_hi:[1,0]
	v_pk_mul_f32 v[194:195], v[136:137], v[194:195]
	v_pk_mul_f32 v[196:197], v[134:135], v[192:193]
	v_pk_mul_f32 v[198:199], v[132:133], v[198:199]
	s_and_b64 vcc, exec, s[6:7]
	v_pk_mul_f32 v[200:201], v[130:131], v[200:201]
	s_cbranch_vccnz .LBB0_366
	ds_bpermute_b32 v192, v212, v196
	ds_bpermute_b32 v193, v212, v197
	ds_bpermute_b32 v214, v212, v200
	ds_bpermute_b32 v216, v212, v194
	ds_bpermute_b32 v217, v212, v195
	ds_bpermute_b32 v215, v212, v201
	ds_bpermute_b32 v218, v212, v198
	ds_bpermute_b32 v219, v212, v199
	s_waitcnt lgkmcnt(6)
	v_pk_mul_f32 v[192:193], v[188:189], v[192:193]
	s_waitcnt lgkmcnt(3)
	v_pk_mul_f32 v[216:217], v[186:187], v[216:217]
	v_pk_fma_f32 v[196:197], v[142:143], v[196:197], v[192:193]
	s_waitcnt lgkmcnt(2)
	v_pk_mul_f32 v[192:193], v[182:183], v[214:215]
	s_waitcnt lgkmcnt(0)
	v_pk_mul_f32 v[214:215], v[184:185], v[218:219]
	v_pk_fma_f32 v[194:195], v[144:145], v[194:195], v[216:217]
	v_pk_fma_f32 v[198:199], v[140:141], v[198:199], v[214:215]
	v_pk_fma_f32 v[200:201], v[138:139], v[200:201], v[192:193]
.LBB0_366:
	v_ashrrev_i32_e32 v191, 31, v190
	v_lshlrev_b64 v[190:191], 8, v[190:191]
	v_lshl_add_u64 v[190:191], s[34:35], 0, v[190:191]
	v_mov_b32_e32 v192, v176
	v_mov_b32_e32 v193, v176
	v_lshl_add_u64 v[190:191], v[190:191], 0, s[50:51]
	v_pk_mul_f32 v[214:215], v[192:193], v[194:195]
	v_pk_mul_f32 v[194:195], v[176:177], v[196:197]
	v_pk_mul_f32 v[198:199], v[192:193], v[198:199]
	v_pk_mul_f32 v[196:197], v[176:177], v[200:201]
	v_lshl_add_u64 v[190:191], v[172:173], 1, v[190:191]
	v_cvt_pk_bf16_f32 v194, v194, v195
	v_cvt_pk_bf16_f32 v195, v214, v215
	v_cvt_pk_bf16_f32 v196, v196, v197
	v_cvt_pk_bf16_f32 v197, v198, v199
	global_store_dwordx4 v[190:191], v[194:197], off
	ds_read_b128 v[194:197], v213 offset:3088
	s_waitcnt lgkmcnt(0)
	v_mov_b32_e32 v198, v195
	v_mov_b32_e32 v199, v196
	v_mov_b32_e32 v195, v197
	v_pk_add_f32 v[194:195], v[198:199], v[194:195]
	s_nop 0
	v_add_f32_e32 v0, v194, v195
	v_fmamk_f32 v0, v0, 0x3c000000, v203
	v_cmp_gt_f32_e32 vcc, s89, v0
	v_mul_f32_e32 v175, 0x4b800000, v0
	s_nop 0
	v_cndmask_b32_e32 v0, v0, v175, vcc
	v_rsq_f32_e32 v0, v0
	s_nop 0
	v_mul_f32_e32 v175, 0x45800000, v0
	v_cndmask_b32_e32 v0, v0, v175, vcc
	v_pk_mul_f32 v[196:197], v[14:15], v[0:1] op_sel_hi:[1,0]
	v_pk_mul_f32 v[194:195], v[16:17], v[0:1] op_sel_hi:[1,0]
	v_pk_mul_f32 v[200:201], v[10:11], v[0:1] op_sel_hi:[1,0]
	v_pk_mul_f32 v[198:199], v[12:13], v[0:1] op_sel_hi:[1,0]
	v_pk_mul_f32 v[194:195], v[136:137], v[194:195]
	v_pk_mul_f32 v[196:197], v[134:135], v[196:197]
	v_pk_mul_f32 v[198:199], v[132:133], v[198:199]
	v_pk_mul_f32 v[200:201], v[130:131], v[200:201]
	s_and_b64 vcc, exec, s[6:7]
	s_cbranch_vccnz .LBB0_368
	ds_bpermute_b32 v214, v212, v196
	ds_bpermute_b32 v215, v212, v197
	ds_bpermute_b32 v218, v212, v194
	ds_bpermute_b32 v219, v212, v195
	ds_bpermute_b32 v216, v212, v200
	ds_bpermute_b32 v217, v212, v201
	ds_bpermute_b32 v220, v212, v198
	ds_bpermute_b32 v221, v212, v199
	s_waitcnt lgkmcnt(6)
	v_pk_mul_f32 v[188:189], v[188:189], v[214:215]
	s_waitcnt lgkmcnt(4)
	v_pk_mul_f32 v[186:187], v[186:187], v[218:219]
	v_pk_fma_f32 v[196:197], v[142:143], v[196:197], v[188:189]
	v_pk_fma_f32 v[194:195], v[144:145], v[194:195], v[186:187]
	s_waitcnt lgkmcnt(2)
	v_pk_mul_f32 v[142:143], v[182:183], v[216:217]
	s_waitcnt lgkmcnt(0)
	v_pk_mul_f32 v[144:145], v[184:185], v[220:221]
	v_pk_fma_f32 v[200:201], v[138:139], v[200:201], v[142:143]
	v_pk_fma_f32 v[198:199], v[140:141], v[198:199], v[144:145]
.LBB0_368:
	v_pk_mul_f32 v[140:141], v[192:193], v[194:195]
	v_pk_mul_f32 v[138:139], v[176:177], v[196:197]
	v_pk_mul_f32 v[142:143], v[192:193], v[198:199]
	v_cvt_pk_bf16_f32 v138, v138, v139
	v_cvt_pk_bf16_f32 v139, v140, v141
	v_cvt_pk_bf16_f32 v141, v142, v143
	v_add_co_u32_e32 v142, vcc, 0x800000, v190
	v_pk_mul_f32 v[144:145], v[176:177], v[200:201]
	s_nop 0
	v_addc_co_u32_e32 v143, vcc, 0, v191, vcc
	v_cvt_pk_bf16_f32 v140, v144, v145
	s_and_b64 vcc, exec, s[6:7]
	v_add_u32_e32 v186, 0xb0, v174
	global_store_dwordx4 v[142:143], v[138:141], off
	s_cbranch_vccnz .LBB0_370
	s_waitcnt vmcnt(2)
	v_mov_b32_e32 v192, v178
	v_mov_b32_e32 v193, v178
	v_pk_mul_f32 v[182:183], v[192:193], v[224:225]
	v_pk_mul_f32 v[184:185], v[178:179], v[222:223]
	v_pk_mul_f32 v[180:181], v[192:193], v[228:229]
	v_pk_mul_f32 v[178:179], v[178:179], v[226:227]
	v_mov_b32_e32 v138, v230
	v_mov_b32_e32 v139, v231
	v_mov_b32_e32 v140, v232
	v_mov_b32_e32 v141, v233
	v_mov_b32_e32 v142, v234
	v_mov_b32_e32 v143, v235
	v_mov_b32_e32 v144, v236
	v_mov_b32_e32 v145, v237
	s_branch .LBB0_371

; #define LAS __attribute__((address_space(3)))
;     __device__ __forceinline__ void operator()(const f32x4 (&acc)[2][2][4][2], const Unit& u, int wr, int wc, int fr, int fq) const {
;     ...
; #pragma unroll
;                 for (int bj = 0; bj < 2; ++bj) {
;                     const f32x4 t4 = *(const LAS f32x4*)(T + ((wr * 128 + ai * 64 + m * 16 + fr) * 2 + bj) * 4);
;                     const float rstd = rsqrtf(((t4[0] + t4[1]) + (t4[2] + t4[3])) * (1.0f / 128.0f) + EPSN);
;                     f32x4 v0 = acc[ai][bj][m][0] * rstd * gm[0], v1 = acc[ai][bj][m][1] * rstd * gm[1];
;                     if (dorope) {
;                         f32x4 p0, p1;
; #pragma unroll
;                         for (int e = 0; e < 4; ++e) { p0[e] = __shfl_xor(v0[e], 32); p1[e] = __shfl_xor(v1[e], 32); }
;                         v0 = v0 * cs[0] + p0 * sn[0]; v1 = v1 * cs[1] + p1 * sn[1];
.LBB0_371:
	ds_read_b128 v[188:191], v213 offset:3584
	s_waitcnt lgkmcnt(0)
	v_mov_b32_e32 v192, v189
	v_mov_b32_e32 v193, v190
	v_mov_b32_e32 v189, v191
	v_pk_add_f32 v[188:189], v[192:193], v[188:189]
	s_nop 0
	v_add_f32_e32 v0, v188, v189
	v_fmamk_f32 v0, v0, 0x3c000000, v203
	v_mul_f32_e32 v175, 0x4b800000, v0
	v_cmp_gt_f32_e32 vcc, s89, v0
	s_nop 1
	v_cndmask_b32_e32 v0, v0, v175, vcc
	v_rsq_f32_e32 v0, v0
	s_nop 0
	v_mul_f32_e32 v175, 0x45800000, v0
	v_cndmask_b32_e32 v0, v0, v175, vcc
	v_pk_mul_f32 v[188:189], v[22:23], v[0:1] op_sel_hi:[1,0]
	v_pk_mul_f32 v[190:191], v[24:25], v[0:1] op_sel_hi:[1,0]
	v_pk_mul_f32 v[196:197], v[18:19], v[0:1] op_sel_hi:[1,0]
	v_pk_mul_f32 v[194:195], v[20:21], v[0:1] op_sel_hi:[1,0]
	v_pk_mul_f32 v[190:191], v[136:137], v[190:191]
	v_pk_mul_f32 v[192:193], v[134:135], v[188:189]
	v_pk_mul_f32 v[194:195], v[132:133], v[194:195]
	s_and_b64 vcc, exec, s[6:7]
	v_pk_mul_f32 v[196:197], v[130:131], v[196:197]
	s_cbranch_vccnz .LBB0_373
	ds_bpermute_b32 v188, v212, v192
	ds_bpermute_b32 v189, v212, v193
	ds_bpermute_b32 v198, v212, v196
	ds_bpermute_b32 v200, v212, v190
	ds_bpermute_b32 v201, v212, v191
	ds_bpermute_b32 v199, v212, v197
	ds_bpermute_b32 v214, v212, v194
	ds_bpermute_b32 v215, v212, v195
	s_waitcnt lgkmcnt(6)
	v_pk_mul_f32 v[188:189], v[184:185], v[188:189]
	s_waitcnt lgkmcnt(3)
	v_pk_mul_f32 v[200:201], v[182:183], v[200:201]
	v_pk_fma_f32 v[192:193], v[142:143], v[192:193], v[188:189]
	s_waitcnt lgkmcnt(2)
	v_pk_mul_f32 v[188:189], v[178:179], v[198:199]
	s_waitcnt lgkmcnt(0)
	v_pk_mul_f32 v[198:199], v[180:181], v[214:215]
	v_pk_fma_f32 v[190:191], v[144:145], v[190:191], v[200:201]
	v_pk_fma_f32 v[194:195], v[140:141], v[194:195], v[198:199]
	v_pk_fma_f32 v[196:197], v[138:139], v[196:197], v[188:189]
.LBB0_373:
	v_ashrrev_i32_e32 v187, 31, v186
	v_lshlrev_b64 v[186:187], 8, v[186:187]
	v_lshl_add_u64 v[186:187], s[34:35], 0, v[186:187]
	v_mov_b32_e32 v188, v176
	v_mov_b32_e32 v189, v176
	v_lshl_add_u64 v[186:187], v[186:187], 0, s[50:51]
	v_pk_mul_f32 v[198:199], v[188:189], v[190:191]
	v_pk_mul_f32 v[190:191], v[176:177], v[192:193]
	v_pk_mul_f32 v[194:195], v[188:189], v[194:195]
	v_pk_mul_f32 v[192:193], v[176:177], v[196:197]
	v_lshl_add_u64 v[186:187], v[172:173], 1, v[186:187]
	v_cvt_pk_bf16_f32 v190, v190, v191
	v_cvt_pk_bf16_f32 v191, v198, v199
	v_cvt_pk_bf16_f32 v192, v192, v193
	v_cvt_pk_bf16_f32 v193, v194, v195
	global_store_dwordx4 v[186:187], v[190:193], off
	ds_read_b128 v[190:193], v213 offset:3600
	s_waitcnt lgkmcnt(0)
	v_mov_b32_e32 v194, v191
	v_mov_b32_e32 v195, v192
	v_mov_b32_e32 v191, v193
	v_pk_add_f32 v[190:191], v[194:195], v[190:191]
	s_nop 0
	v_add_f32_e32 v0, v190, v191
	v_fmamk_f32 v0, v0, 0x3c000000, v203
	v_cmp_gt_f32_e32 vcc, s89, v0
	v_mul_f32_e32 v173, 0x4b800000, v0
	s_nop 0
	v_cndmask_b32_e32 v0, v0, v173, vcc
	v_rsq_f32_e32 v0, v0
	s_nop 0
	v_mul_f32_e32 v173, 0x45800000, v0
	v_cndmask_b32_e32 v0, v0, v173, vcc
	v_pk_mul_f32 v[190:191], v[6:7], v[0:1] op_sel_hi:[1,0]
	v_pk_mul_f32 v[192:193], v[8:9], v[0:1] op_sel_hi:[1,0]
	v_pk_mul_f32 v[190:191], v[134:135], v[190:191]
	v_pk_mul_f32 v[136:137], v[136:137], v[192:193]
	v_pk_mul_f32 v[192:193], v[2:3], v[0:1] op_sel_hi:[1,0]
	v_pk_mul_f32 v[134:135], v[4:5], v[0:1] op_sel_hi:[1,0]
	v_pk_mul_f32 v[192:193], v[130:131], v[192:193]
	v_pk_mul_f32 v[134:135], v[132:133], v[134:135]
	s_and_b64 vcc, exec, s[6:7]
	s_cbranch_vccnz .LBB0_375
	ds_bpermute_b32 v130, v212, v190
	ds_bpermute_b32 v131, v212, v191
	ds_bpermute_b32 v132, v212, v192
	ds_bpermute_b32 v194, v212, v136
	ds_bpermute_b32 v195, v212, v137
	ds_bpermute_b32 v133, v212, v193
	ds_bpermute_b32 v196, v212, v134
	ds_bpermute_b32 v197, v212, v135
	s_waitcnt lgkmcnt(6)
	v_pk_mul_f32 v[130:131], v[184:185], v[130:131]
	s_waitcnt lgkmcnt(3)
	v_pk_mul_f32 v[182:183], v[182:183], v[194:195]
	v_pk_fma_f32 v[190:191], v[142:143], v[190:191], v[130:131]
	s_waitcnt lgkmcnt(2)
	v_pk_mul_f32 v[130:131], v[178:179], v[132:133]
	s_waitcnt lgkmcnt(0)
	v_pk_mul_f32 v[132:133], v[180:181], v[196:197]
	v_pk_fma_f32 v[136:137], v[144:145], v[136:137], v[182:183]
	v_pk_fma_f32 v[134:135], v[140:141], v[134:135], v[132:133]
	v_pk_fma_f32 v[192:193], v[138:139], v[192:193], v[130:131]
